# K-loops: removed the redundant s_setprio 0 / s_setprio 1 pair in the middle of each 32-MFMA block (priority unchanged, two fewer issue slots between MFMAs)
# speedup vs baseline: 1.0328x; 1.0328x over previous
; #define PG8_STAGE(bufoff, gbase, voff) do { _Pragma("unroll") for (int _i = 0; _i < 2; ++_i) \
;         __builtin_amdgcn_global_load_lds((const unsigned*)((const char*)(gbase) + (voff)[_i]), (LAS unsigned*)(lds + (bufoff) + ldsw + _i * 8192), 16, 0, 0); } while (0)
; #define PG8_LDA(dst, b, h) do { _Pragma("unroll") for (int m = 0; m < 4; ++m) _Pragma("unroll") for (int k = 0; k < 2; ++k) dst[m][k] = *(const LAS bf16x8*)(lds + PG8_SA(b, h) + aoff + m * 2048 + k * 1024); } while (0)
; #define PG8_LDB(dst, b, h) do { _Pragma("unroll") for (int n = 0; n < 2; ++n) _Pragma("unroll") for (int k = 0; k < 2; ++k) dst[n][k] = *(const LAS bf16x8*)(lds + PG8_SB(b, h) + boff + n * 2048 + k * 1024); } while (0)
; #define PG8_MMA(ai, bj, At, Bt) do { __builtin_amdgcn_s_setprio(1); _Pragma("unroll") for (int m = 0; m < 4; ++m) _Pragma("unroll") for (int n = 0; n < 2; ++n) _Pragma("unroll") for (int k = 0; k < 2; ++k) \
;         acc[ai][bj][m][n] = __builtin_amdgcn_mfma_f32_16x16x32_bf16(Bt[n][k], At[m][k], acc[ai][bj][m][n], 0, 0, 0); __builtin_amdgcn_s_setprio(0); } while (0)
; #define PG8_WAIT_V(n) asm volatile("s_waitcnt vmcnt(" #n ")" ::: "memory")
; #define PG8_WAIT_L(n) asm volatile("s_waitcnt lgkmcnt(" #n ")" ::: "memory")
; #define PG8_BAR __builtin_amdgcn_s_barrier()
; #define PG8_SCHED __builtin_amdgcn_sched_barrier(0)
; template <class Epi, bool ALIGN_EPI>
; __device__ __forceinline__ void gemm_phase(LAS unsigned char* lds, const Gemm g, int G, int cid, const Epi& E) {
;     ...
;             const char* a1 = cA + (size_t)(t + 1) * kA;
;             const char* a2 = last ? nA : cA + (size_t)(t + 2) * kA; const char* b2 = last ? nB : cB + (size_t)(t + 2) * kB;
;             const char* a3 = a2 + kA; const char* b3 = b2 + kB;
;             PG8_LDB(B0, 0, 0); PG8_LDB(B1, 0, 1); PG8_SCHED; PG8_LDA(At, 0, 0); PG8_STAGE(PG8_SA(1, 1), a1 + hA, voffA);
;             PG8_WAIT_V(8); PG8_WAIT_L(0); PG8_BAR; PG8_MMA(0, 0, At, B0); PG8_MMA(0, 1, At, B1); PG8_BAR; PG8_SCHED;
;             PG8_LDA(At, 0, 1); PG8_STAGE(PG8_SB(0, 0), b2, voffB); PG8_STAGE(PG8_SB(0, 1), b2 + hB, voffB); PG8_STAGE(PG8_SA(0, 0), a2, voffA);
;             PG8_WAIT_V(8); PG8_WAIT_L(0); PG8_BAR; PG8_MMA(1, 0, At, B0); PG8_MMA(1, 1, At, B1); PG8_BAR; PG8_SCHED;
.LBB0_169:
	s_add_u32 s44, s50, 0x100
	s_addc_u32 s45, s51, 0
	s_add_i32 s6, 0, 0x10000
	s_cmp_eq_u32 s79, 4
	s_cselect_b32 s55, s43, s45
	s_cselect_b32 s54, s42, s44
	s_cselect_b32 s53, s30, s78
	s_cselect_b32 s52, s76, s77
	s_add_i32 s86, 0, 0x14000
	v_add_u32_e32 v84, s6, v212
	v_add_u32_e32 v100, s86, v212
	ds_read_b128 v[68:71], v84
	ds_read_b128 v[76:79], v84 offset:1024
	ds_read_b128 v[80:83], v84 offset:2048
	ds_read_b128 v[84:87], v84 offset:3072
	ds_read_b128 v[88:91], v100
	ds_read_b128 v[92:95], v100 offset:1024
	ds_read_b128 v[96:99], v100 offset:2048
	ds_read_b128 v[100:103], v100 offset:3072
	v_lshl_add_u64 v[198:199], s[50:51], 0, v[184:185]
	s_add_i32 m0, s24, 0xc000
	ds_read_b128 v[164:167], v214
	ds_read_b128 v[168:171], v214 offset:1024
	ds_read_b128 v[172:175], v214 offset:2048
	ds_read_b128 v[176:179], v214 offset:3072
	ds_read_b128 v[188:191], v214 offset:4096
	ds_read_b128 v[206:209], v214 offset:5120
	ds_read_b128 v[216:219], v214 offset:6144
	ds_read_b128 v[220:223], v214 offset:7168
	global_load_lds_dwordx4 v[198:199], off
	v_lshl_add_u64 v[198:199], s[50:51], 0, v[186:187]
	s_add_i32 m0, s24, 0xe000
	s_nop 0
	global_load_lds_dwordx4 v[198:199], off
	s_waitcnt vmcnt(8)
	s_waitcnt lgkmcnt(0)
	s_barrier
	s_setprio 1
	s_waitcnt lgkmcnt(0)
	v_mfma_f32_16x16x32_bf16 v[160:163], v[68:71], v[164:167], v[160:163]
	v_mfma_f32_16x16x32_bf16 v[156:159], v[80:83], v[164:167], v[156:159]
	v_mfma_f32_16x16x32_bf16 v[144:147], v[68:71], v[172:175], v[144:147]
	v_mfma_f32_16x16x32_bf16 v[140:143], v[80:83], v[172:175], v[140:143]
	v_mfma_f32_16x16x32_bf16 v[124:127], v[68:71], v[188:191], v[124:127]
	v_mfma_f32_16x16x32_bf16 v[120:123], v[80:83], v[188:191], v[120:123]
	v_mfma_f32_16x16x32_bf16 v[108:111], v[68:71], v[216:219], v[108:111]
	v_mfma_f32_16x16x32_bf16 v[104:107], v[80:83], v[216:219], v[104:107]
	v_mfma_f32_16x16x32_bf16 v[160:163], v[76:79], v[168:171], v[160:163]
	v_mfma_f32_16x16x32_bf16 v[156:159], v[84:87], v[168:171], v[156:159]
	v_mfma_f32_16x16x32_bf16 v[144:147], v[76:79], v[176:179], v[144:147]
	v_mfma_f32_16x16x32_bf16 v[140:143], v[84:87], v[176:179], v[140:143]
	v_mfma_f32_16x16x32_bf16 v[124:127], v[76:79], v[206:209], v[124:127]
	v_mfma_f32_16x16x32_bf16 v[120:123], v[84:87], v[206:209], v[120:123]
	v_mfma_f32_16x16x32_bf16 v[108:111], v[76:79], v[220:223], v[108:111]
	v_mfma_f32_16x16x32_bf16 v[104:107], v[84:87], v[220:223], v[104:107]
	v_mfma_f32_16x16x32_bf16 v[152:155], v[88:91], v[164:167], v[152:155]
	v_mfma_f32_16x16x32_bf16 v[148:151], v[96:99], v[164:167], v[148:151]
	v_mfma_f32_16x16x32_bf16 v[132:135], v[88:91], v[172:175], v[132:135]
	v_mfma_f32_16x16x32_bf16 v[128:131], v[96:99], v[172:175], v[128:131]
	v_mfma_f32_16x16x32_bf16 v[116:119], v[88:91], v[188:191], v[116:119]
	v_mfma_f32_16x16x32_bf16 v[112:115], v[96:99], v[188:191], v[112:115]
	v_mfma_f32_16x16x32_bf16 v[72:75], v[88:91], v[216:219], v[72:75]
	v_mfma_f32_16x16x32_bf16 v[64:67], v[96:99], v[216:219], v[64:67]
	v_mfma_f32_16x16x32_bf16 v[152:155], v[92:95], v[168:171], v[152:155]
	v_mfma_f32_16x16x32_bf16 v[148:151], v[100:103], v[168:171], v[148:151]
	v_mfma_f32_16x16x32_bf16 v[132:135], v[92:95], v[176:179], v[132:135]
	v_mfma_f32_16x16x32_bf16 v[128:131], v[100:103], v[176:179], v[128:131]
	v_mfma_f32_16x16x32_bf16 v[116:119], v[92:95], v[206:209], v[116:119]
	v_mfma_f32_16x16x32_bf16 v[112:115], v[100:103], v[206:209], v[112:115]
	v_mfma_f32_16x16x32_bf16 v[72:75], v[92:95], v[220:223], v[72:75]
	v_mfma_f32_16x16x32_bf16 v[64:67], v[100:103], v[220:223], v[64:67]
	s_setprio 0
	s_barrier
	s_add_i32 s6, s6, s23
	v_lshl_add_u64 v[198:199], s[52:53], 0, v[138:139]
	s_mov_b32 m0, s6
	ds_read_b128 v[164:167], v214 offset:16384
	ds_read_b128 v[168:171], v214 offset:17408
	ds_read_b128 v[172:175], v214 offset:18432
	ds_read_b128 v[176:179], v214 offset:19456
	ds_read_b128 v[188:191], v214 offset:20480
	ds_read_b128 v[206:209], v214 offset:21504
	ds_read_b128 v[216:219], v214 offset:22528
	ds_read_b128 v[220:223], v214 offset:23552
	global_load_lds_dwordx4 v[198:199], off
	s_add_i32 m0, s6, 0x2000
	s_add_u32 s6, s52, 0x2000
	v_lshl_add_u64 v[198:199], s[52:53], 0, v[136:137]
	s_addc_u32 s7, s53, 0
	s_add_i32 s50, s86, s23
	global_load_lds_dwordx4 v[198:199], off
	v_lshl_add_u64 v[198:199], s[6:7], 0, v[138:139]
	s_mov_b32 m0, s50
	v_lshl_add_u64 v[200:201], s[54:55], 0, v[180:181]
	global_load_lds_dwordx4 v[198:199], off
	v_lshl_add_u64 v[198:199], s[6:7], 0, v[136:137]
	s_add_i32 m0, s50, 0x2000
	s_nop 0
	global_load_lds_dwordx4 v[198:199], off
	v_lshl_add_u64 v[198:199], s[54:55], 0, v[182:183]
	s_mov_b32 m0, s24
	s_nop 0
	global_load_lds_dwordx4 v[198:199], off
	s_mov_b32 m0, s25
	s_nop 0
	global_load_lds_dwordx4 v[200:201], off
	s_waitcnt vmcnt(8)
	s_waitcnt lgkmcnt(0)
	s_barrier
; #define PG8_STAGE(bufoff, gbase, voff) do { _Pragma("unroll") for (int _i = 0; _i < 2; ++_i) \
;         __builtin_amdgcn_global_load_lds((const unsigned*)((const char*)(gbase) + (voff)[_i]), (LAS unsigned*)(lds + (bufoff) + ldsw + _i * 8192), 16, 0, 0); } while (0)
; #define PG8_LDA(dst, b, h) do { _Pragma("unroll") for (int m = 0; m < 4; ++m) _Pragma("unroll") for (int k = 0; k < 2; ++k) dst[m][k] = *(const LAS bf16x8*)(lds + PG8_SA(b, h) + aoff + m * 2048 + k * 1024); } while (0)
; #define PG8_LDB(dst, b, h) do { _Pragma("unroll") for (int n = 0; n < 2; ++n) _Pragma("unroll") for (int k = 0; k < 2; ++k) dst[n][k] = *(const LAS bf16x8*)(lds + PG8_SB(b, h) + boff + n * 2048 + k * 1024); } while (0)
; #define PG8_MMA(ai, bj, At, Bt) do { __builtin_amdgcn_s_setprio(1); _Pragma("unroll") for (int m = 0; m < 4; ++m) _Pragma("unroll") for (int n = 0; n < 2; ++n) _Pragma("unroll") for (int k = 0; k < 2; ++k) \
;         acc[ai][bj][m][n] = __builtin_amdgcn_mfma_f32_16x16x32_bf16(Bt[n][k], At[m][k], acc[ai][bj][m][n], 0, 0, 0); __builtin_amdgcn_s_setprio(0); } while (0)
; #define PG8_WAIT_V(n) asm volatile("s_waitcnt vmcnt(" #n ")" ::: "memory")
; #define PG8_WAIT_L(n) asm volatile("s_waitcnt lgkmcnt(" #n ")" ::: "memory")
; #define PG8_BAR __builtin_amdgcn_s_barrier()
; #define PG8_SCHED __builtin_amdgcn_sched_barrier(0)
; template <class Epi, bool ALIGN_EPI>
; __device__ __forceinline__ void gemm_phase(LAS unsigned char* lds, const Gemm g, int G, int cid, const Epi& E) {
;     ...
;             PG8_WAIT_V(8); PG8_WAIT_L(0); PG8_BAR; PG8_MMA(1, 0, At, B0); PG8_MMA(1, 1, At, B1); PG8_BAR; PG8_SCHED;
;             PG8_LDB(B0, 1, 0); PG8_LDB(B1, 1, 1); PG8_SCHED; PG8_LDA(At, 1, 0); PG8_STAGE(PG8_SA(0, 1), a2 + hA, voffA);
;             PG8_WAIT_V(8); PG8_WAIT_L(0); PG8_BAR; PG8_MMA(0, 0, At, B0); PG8_MMA(0, 1, At, B1); PG8_BAR; PG8_SCHED;
	s_setprio 1
	s_waitcnt lgkmcnt(0)
	v_mfma_f32_16x16x32_bf16 v[60:63], v[68:71], v[164:167], v[60:63]
	v_mfma_f32_16x16x32_bf16 v[56:59], v[80:83], v[164:167], v[56:59]
	v_mfma_f32_16x16x32_bf16 v[44:47], v[68:71], v[172:175], v[44:47]
	v_mfma_f32_16x16x32_bf16 v[40:43], v[80:83], v[172:175], v[40:43]
	v_mfma_f32_16x16x32_bf16 v[28:31], v[68:71], v[188:191], v[28:31]
	v_mfma_f32_16x16x32_bf16 v[24:27], v[80:83], v[188:191], v[24:27]
	v_mfma_f32_16x16x32_bf16 v[12:15], v[68:71], v[216:219], v[12:15]
	v_mfma_f32_16x16x32_bf16 v[8:11], v[80:83], v[216:219], v[8:11]
	v_mfma_f32_16x16x32_bf16 v[60:63], v[76:79], v[168:171], v[60:63]
	v_mfma_f32_16x16x32_bf16 v[56:59], v[84:87], v[168:171], v[56:59]
	v_mfma_f32_16x16x32_bf16 v[44:47], v[76:79], v[176:179], v[44:47]
	v_mfma_f32_16x16x32_bf16 v[40:43], v[84:87], v[176:179], v[40:43]
	v_mfma_f32_16x16x32_bf16 v[28:31], v[76:79], v[206:209], v[28:31]
	v_mfma_f32_16x16x32_bf16 v[24:27], v[84:87], v[206:209], v[24:27]
	v_mfma_f32_16x16x32_bf16 v[12:15], v[76:79], v[220:223], v[12:15]
	v_mfma_f32_16x16x32_bf16 v[8:11], v[84:87], v[220:223], v[8:11]
	v_mfma_f32_16x16x32_bf16 v[52:55], v[88:91], v[164:167], v[52:55]
	v_mfma_f32_16x16x32_bf16 v[48:51], v[96:99], v[164:167], v[48:51]
	v_mfma_f32_16x16x32_bf16 v[36:39], v[88:91], v[172:175], v[36:39]
	v_mfma_f32_16x16x32_bf16 v[32:35], v[96:99], v[172:175], v[32:35]
	v_mfma_f32_16x16x32_bf16 v[20:23], v[88:91], v[188:191], v[20:23]
	v_mfma_f32_16x16x32_bf16 v[16:19], v[96:99], v[188:191], v[16:19]
	v_mfma_f32_16x16x32_bf16 v[4:7], v[88:91], v[216:219], v[4:7]
	v_mfma_f32_16x16x32_bf16 v[0:3], v[96:99], v[216:219], v[0:3]
	v_mfma_f32_16x16x32_bf16 v[52:55], v[92:95], v[168:171], v[52:55]
	v_mfma_f32_16x16x32_bf16 v[48:51], v[100:103], v[168:171], v[48:51]
	v_mfma_f32_16x16x32_bf16 v[36:39], v[92:95], v[176:179], v[36:39]
	v_mfma_f32_16x16x32_bf16 v[32:35], v[100:103], v[176:179], v[32:35]
	v_mfma_f32_16x16x32_bf16 v[20:23], v[92:95], v[206:209], v[20:23]
	v_mfma_f32_16x16x32_bf16 v[16:19], v[100:103], v[206:209], v[16:19]
	v_mfma_f32_16x16x32_bf16 v[4:7], v[92:95], v[220:223], v[4:7]
	v_mfma_f32_16x16x32_bf16 v[0:3], v[100:103], v[220:223], v[0:3]
	s_setprio 0
	s_barrier
	s_add_i32 s50, 0, 0x18000
	s_add_i32 s51, 0, 0x1c000
	v_add_u32_e32 v84, s50, v212
	v_add_u32_e32 v100, s51, v212
	ds_read_b128 v[68:71], v84
	ds_read_b128 v[76:79], v84 offset:1024
	ds_read_b128 v[80:83], v84 offset:2048
	ds_read_b128 v[84:87], v84 offset:3072
	ds_read_b128 v[88:91], v100
	ds_read_b128 v[92:95], v100 offset:1024
	ds_read_b128 v[96:99], v100 offset:2048
	ds_read_b128 v[100:103], v100 offset:3072
	s_add_u32 s6, s54, 0x84000
	s_addc_u32 s7, s55, 0
	s_mov_b32 m0, s56
	v_lshl_add_u64 v[210:211], s[6:7], 0, v[182:183]
	ds_read_b128 v[164:167], v214 offset:32768
	ds_read_b128 v[168:171], v214 offset:33792
	ds_read_b128 v[172:175], v214 offset:34816
	ds_read_b128 v[176:179], v214 offset:35840
	ds_read_b128 v[188:191], v214 offset:36864
	ds_read_b128 v[206:209], v214 offset:37888
	ds_read_b128 v[216:219], v214 offset:38912
	ds_read_b128 v[220:223], v214 offset:39936
	global_load_lds_dwordx4 v[210:211], off
	v_lshl_add_u64 v[210:211], s[6:7], 0, v[180:181]
	s_mov_b32 m0, s57
	s_nop 0
	global_load_lds_dwordx4 v[210:211], off
	s_waitcnt vmcnt(8)
	s_waitcnt lgkmcnt(0)
	s_barrier
	s_setprio 1
	s_waitcnt lgkmcnt(0)
	v_mfma_f32_16x16x32_bf16 v[160:163], v[68:71], v[164:167], v[160:163]
	v_mfma_f32_16x16x32_bf16 v[156:159], v[80:83], v[164:167], v[156:159]
	v_mfma_f32_16x16x32_bf16 v[144:147], v[68:71], v[172:175], v[144:147]
	v_mfma_f32_16x16x32_bf16 v[140:143], v[80:83], v[172:175], v[140:143]
	v_mfma_f32_16x16x32_bf16 v[124:127], v[68:71], v[188:191], v[124:127]
	v_mfma_f32_16x16x32_bf16 v[120:123], v[80:83], v[188:191], v[120:123]
	v_mfma_f32_16x16x32_bf16 v[108:111], v[68:71], v[216:219], v[108:111]
	v_mfma_f32_16x16x32_bf16 v[104:107], v[80:83], v[216:219], v[104:107]
	v_mfma_f32_16x16x32_bf16 v[160:163], v[76:79], v[168:171], v[160:163]
	v_mfma_f32_16x16x32_bf16 v[156:159], v[84:87], v[168:171], v[156:159]
	v_mfma_f32_16x16x32_bf16 v[144:147], v[76:79], v[176:179], v[144:147]
	v_mfma_f32_16x16x32_bf16 v[140:143], v[84:87], v[176:179], v[140:143]
	v_mfma_f32_16x16x32_bf16 v[124:127], v[76:79], v[206:209], v[124:127]
	v_mfma_f32_16x16x32_bf16 v[120:123], v[84:87], v[206:209], v[120:123]
	v_mfma_f32_16x16x32_bf16 v[108:111], v[76:79], v[220:223], v[108:111]
	v_mfma_f32_16x16x32_bf16 v[104:107], v[84:87], v[220:223], v[104:107]
	v_mfma_f32_16x16x32_bf16 v[152:155], v[88:91], v[164:167], v[152:155]
	v_mfma_f32_16x16x32_bf16 v[148:151], v[96:99], v[164:167], v[148:151]
	v_mfma_f32_16x16x32_bf16 v[132:135], v[88:91], v[172:175], v[132:135]
	v_mfma_f32_16x16x32_bf16 v[128:131], v[96:99], v[172:175], v[128:131]
	v_mfma_f32_16x16x32_bf16 v[116:119], v[88:91], v[188:191], v[116:119]
	v_mfma_f32_16x16x32_bf16 v[112:115], v[96:99], v[188:191], v[112:115]
	v_mfma_f32_16x16x32_bf16 v[72:75], v[88:91], v[216:219], v[72:75]
	v_mfma_f32_16x16x32_bf16 v[64:67], v[96:99], v[216:219], v[64:67]
	v_mfma_f32_16x16x32_bf16 v[152:155], v[92:95], v[168:171], v[152:155]
	v_mfma_f32_16x16x32_bf16 v[148:151], v[100:103], v[168:171], v[148:151]
	v_mfma_f32_16x16x32_bf16 v[132:135], v[92:95], v[176:179], v[132:135]
	v_mfma_f32_16x16x32_bf16 v[128:131], v[100:103], v[176:179], v[128:131]
	v_mfma_f32_16x16x32_bf16 v[116:119], v[92:95], v[206:209], v[116:119]
	v_mfma_f32_16x16x32_bf16 v[112:115], v[100:103], v[206:209], v[112:115]
	v_mfma_f32_16x16x32_bf16 v[72:75], v[92:95], v[220:223], v[72:75]
	v_mfma_f32_16x16x32_bf16 v[64:67], v[100:103], v[220:223], v[64:67]
	s_setprio 0
	s_barrier
; #define PG8_STAGE(bufoff, gbase, voff) do { _Pragma("unroll") for (int _i = 0; _i < 2; ++_i) \
;         __builtin_amdgcn_global_load_lds((const unsigned*)((const char*)(gbase) + (voff)[_i]), (LAS unsigned*)(lds + (bufoff) + ldsw + _i * 8192), 16, 0, 0); } while (0)
; #define PG8_LDA(dst, b, h) do { _Pragma("unroll") for (int m = 0; m < 4; ++m) _Pragma("unroll") for (int k = 0; k < 2; ++k) dst[m][k] = *(const LAS bf16x8*)(lds + PG8_SA(b, h) + aoff + m * 2048 + k * 1024); } while (0)
; #define PG8_MMA(ai, bj, At, Bt) do { __builtin_amdgcn_s_setprio(1); _Pragma("unroll") for (int m = 0; m < 4; ++m) _Pragma("unroll") for (int n = 0; n < 2; ++n) _Pragma("unroll") for (int k = 0; k < 2; ++k) \
;         acc[ai][bj][m][n] = __builtin_amdgcn_mfma_f32_16x16x32_bf16(Bt[n][k], At[m][k], acc[ai][bj][m][n], 0, 0, 0); __builtin_amdgcn_s_setprio(0); } while (0)
; #define PG8_WAIT_V(n) asm volatile("s_waitcnt vmcnt(" #n ")" ::: "memory")
; #define PG8_WAIT_L(n) asm volatile("s_waitcnt lgkmcnt(" #n ")" ::: "memory")
; #define PG8_BAR __builtin_amdgcn_s_barrier()
; #define PG8_SCHED __builtin_amdgcn_sched_barrier(0)
; template <class Epi, bool ALIGN_EPI>
; __device__ __forceinline__ void gemm_phase(LAS unsigned char* lds, const Gemm g, int G, int cid, const Epi& E) {
;     ...
;         for (int t = 0; t < nt; t += 2) {
;     ...
;             PG8_LDA(At, 1, 1); PG8_STAGE(PG8_SB(1, 0), b3, voffB); PG8_STAGE(PG8_SB(1, 1), b3 + hB, voffB); PG8_STAGE(PG8_SA(1, 0), a3, voffA);
;             PG8_WAIT_V(8); PG8_WAIT_L(0); PG8_BAR; PG8_MMA(1, 0, At, B0); PG8_MMA(1, 1, At, B1); PG8_BAR; PG8_SCHED;
;         }
	s_add_u32 s6, s52, 0x10000
	s_addc_u32 s7, s53, 0
	s_add_i32 s50, s50, s23
	v_lshl_add_u64 v[210:211], s[6:7], 0, v[138:139]
	s_mov_b32 m0, s50
	ds_read_b128 v[164:167], v214 offset:49152
	ds_read_b128 v[168:171], v214 offset:50176
	ds_read_b128 v[172:175], v214 offset:51200
	ds_read_b128 v[176:179], v214 offset:52224
	ds_read_b128 v[188:191], v214 offset:53248
	ds_read_b128 v[206:209], v214 offset:54272
	ds_read_b128 v[216:219], v214 offset:55296
	ds_read_b128 v[220:223], v214 offset:56320
	global_load_lds_dwordx4 v[210:211], off
	s_add_i32 m0, s50, 0x2000
	v_lshl_add_u64 v[210:211], s[6:7], 0, v[136:137]
	s_add_u32 s6, s52, 0x12000
	s_addc_u32 s7, s53, 0
	s_add_i32 s50, s51, s23
	global_load_lds_dwordx4 v[210:211], off
	v_lshl_add_u64 v[210:211], s[6:7], 0, v[138:139]
	s_mov_b32 m0, s50
	v_lshl_add_u64 v[198:199], v[198:199], 0, s[36:37]
	global_load_lds_dwordx4 v[210:211], off
	v_lshl_add_u64 v[210:211], s[6:7], 0, v[136:137]
	s_add_i32 m0, s50, 0x2000
	s_nop 0
	global_load_lds_dwordx4 v[210:211], off
	s_mov_b32 m0, s59
	s_nop 0
	global_load_lds_dwordx4 v[198:199], off
	v_lshl_add_u64 v[198:199], v[200:201], 0, s[36:37]
	s_mov_b32 m0, s72
	s_nop 0
	global_load_lds_dwordx4 v[198:199], off
	s_waitcnt vmcnt(8)
	s_waitcnt lgkmcnt(0)
	s_barrier
	s_setprio 1
	s_waitcnt lgkmcnt(0)
	v_mfma_f32_16x16x32_bf16 v[60:63], v[68:71], v[164:167], v[60:63]
	v_mfma_f32_16x16x32_bf16 v[56:59], v[80:83], v[164:167], v[56:59]
	v_mfma_f32_16x16x32_bf16 v[44:47], v[68:71], v[172:175], v[44:47]
	v_mfma_f32_16x16x32_bf16 v[40:43], v[80:83], v[172:175], v[40:43]
	v_mfma_f32_16x16x32_bf16 v[28:31], v[68:71], v[188:191], v[28:31]
	v_mfma_f32_16x16x32_bf16 v[24:27], v[80:83], v[188:191], v[24:27]
	v_mfma_f32_16x16x32_bf16 v[12:15], v[68:71], v[216:219], v[12:15]
	v_mfma_f32_16x16x32_bf16 v[8:11], v[80:83], v[216:219], v[8:11]
	v_mfma_f32_16x16x32_bf16 v[60:63], v[76:79], v[168:171], v[60:63]
	v_mfma_f32_16x16x32_bf16 v[56:59], v[84:87], v[168:171], v[56:59]
	v_mfma_f32_16x16x32_bf16 v[44:47], v[76:79], v[176:179], v[44:47]
	v_mfma_f32_16x16x32_bf16 v[40:43], v[84:87], v[176:179], v[40:43]
	v_mfma_f32_16x16x32_bf16 v[28:31], v[76:79], v[206:209], v[28:31]
	v_mfma_f32_16x16x32_bf16 v[24:27], v[84:87], v[206:209], v[24:27]
	v_mfma_f32_16x16x32_bf16 v[12:15], v[76:79], v[220:223], v[12:15]
	v_mfma_f32_16x16x32_bf16 v[8:11], v[84:87], v[220:223], v[8:11]
	v_mfma_f32_16x16x32_bf16 v[52:55], v[88:91], v[164:167], v[52:55]
	v_mfma_f32_16x16x32_bf16 v[48:51], v[96:99], v[164:167], v[48:51]
	v_mfma_f32_16x16x32_bf16 v[36:39], v[88:91], v[172:175], v[36:39]
	v_mfma_f32_16x16x32_bf16 v[32:35], v[96:99], v[172:175], v[32:35]
	v_mfma_f32_16x16x32_bf16 v[20:23], v[88:91], v[188:191], v[20:23]
	v_mfma_f32_16x16x32_bf16 v[16:19], v[96:99], v[188:191], v[16:19]
	v_mfma_f32_16x16x32_bf16 v[4:7], v[88:91], v[216:219], v[4:7]
	v_mfma_f32_16x16x32_bf16 v[0:3], v[96:99], v[216:219], v[0:3]
	v_mfma_f32_16x16x32_bf16 v[52:55], v[92:95], v[168:171], v[52:55]
	v_mfma_f32_16x16x32_bf16 v[48:51], v[100:103], v[168:171], v[48:51]
	v_mfma_f32_16x16x32_bf16 v[36:39], v[92:95], v[176:179], v[36:39]
	v_mfma_f32_16x16x32_bf16 v[32:35], v[100:103], v[176:179], v[32:35]
	v_mfma_f32_16x16x32_bf16 v[20:23], v[92:95], v[206:209], v[20:23]
	v_mfma_f32_16x16x32_bf16 v[16:19], v[100:103], v[206:209], v[16:19]
	v_mfma_f32_16x16x32_bf16 v[4:7], v[92:95], v[220:223], v[4:7]
	v_mfma_f32_16x16x32_bf16 v[0:3], v[100:103], v[220:223], v[0:3]
	s_setprio 0
	s_barrier
	s_add_i32 s79, s79, 2
	s_add_u32 s77, s77, 0x20000
	s_addc_u32 s78, s78, 0
	s_cmp_lt_u32 s79, 6
	s_mov_b64 s[50:51], s[44:45]
	s_cbranch_scc1 .LBB0_169
; #define LAS __attribute__((address_space(3)))
;     __device__ __forceinline__ void operator()(const f32x4 (&acc)[2][2][4][2], const Unit& u, int wr, int wc, int fr, int fq, const LAS float*) const {
;         const int row0 = u.pm * BM + wr * 64 + fr, col0 = u.pn * BM + wc * 32 + 8 * fq;
;         f32x4 bv[2][2], sv[2][2];
; #pragma unroll
;         for (int bj = 0; bj < 2; ++bj)
; #pragma unroll
;             for (int n = 0; n < 2; ++n) { bv[bj][n] = HB ? *(const f32x4*)(bias + col0 + bj * HALF + 4 * n) : (f32x4){0.f, 0.f, 0.f, 0.f};
;                                            sv[bj][n] = HB ? *(const f32x4*)(scale + col0 + bj * HALF + 4 * n) : (f32x4){1.f, 1.f, 1.f, 1.f}; }
;         constexpr int NB = HB ? 4 : 2, MB = 4 / (NB / 2);
; #pragma unroll
;         for (int am = 0; am < NB; ++am) { const int ai = am / (NB / 2), m0 = (am % (NB / 2)) * MB;
;             f32x4 xo[4][2][2];
; #pragma unroll
;             for (int m = m0; m < m0 + MB; ++m) { const float* xr = Xs + (size_t)(row0 + ai * HALF + m * 16) * DM + col0;
; #pragma unroll
;                 for (int bj = 0; bj < 2; ++bj) { xo[m][bj][0] = *(const f32x4*)(xr + bj * HALF); xo[m][bj][1] = *(const f32x4*)(xr + bj * HALF + 4); } }
; #pragma unroll
;             for (int m = m0; m < m0 + MB; ++m) { const int row = row0 + ai * HALF + m * 16; float ss = 0.f;
;                 float* xr = X + (size_t)row * DM + col0; bf16_t* xb = XB + (size_t)row * ALD + col0;
; #pragma unroll
;                 for (int bj = 0; bj < 2; ++bj) { f32x4 x0 = xo[m][bj][0], x1 = xo[m][bj][1];
;                     if (HB) { x0 += (acc[ai][bj][m][0] + bv[bj][0]) * sv[bj][0]; x1 += (acc[ai][bj][m][1] + bv[bj][1]) * sv[bj][1]; } else { x0 += acc[ai][bj][m][0]; x1 += acc[ai][bj][m][1]; }
;                     *(f32x4*)(xr + bj * HALF) = x0; *(f32x4*)(xr + bj * HALF + 4) = x1;
;                     ss += (x0[0] * x0[0] + x0[1] * x0[1]) + (x0[2] * x0[2] + x0[3] * x0[3]) + (x1[0] * x1[0] + x1[1] * x1[1]) + (x1[2] * x1[2] + x1[3] * x1[3]);
;                     u32x4 w; w.x = cvt_pk_bf16(x0[0], x0[1]); w.y = cvt_pk_bf16(x0[2], x0[3]); w.z = cvt_pk_bf16(x1[0], x1[1]); w.w = cvt_pk_bf16(x1[2], x1[3]);
;                     if (feeds) *(u32x4*)(xb + bj * HALF) = w; }
;                 ss += __shfl_xor(ss, 16); ss += __shfl_xor(ss, 32);
;                 if (fq == 0 && feeds) part[(size_t)row * NPART + u.pn * 4 + wc] = ss; }
	v_lshl_or_b32 v188, s12, 8, v213
	v_ashrrev_i32_e32 v189, 31, v188
	v_lshl_add_u32 v190, s13, 8, v197
	v_lshlrev_b64 v[198:199], 2, v[188:189]
	v_ashrrev_i32_e32 v191, 31, v190
	v_lshl_add_u64 v[206:207], s[82:83], 0, v[198:199]
	v_lshlrev_b64 v[200:201], 13, v[190:191]
	v_lshl_add_u64 v[68:69], s[28:29], 0, v[198:199]
	v_lshl_add_u64 v[80:81], s[46:47], 0, v[198:199]
	v_lshl_add_u64 v[164:165], v[206:207], 0, v[200:201]
	global_load_dwordx4 v[92:95], v[68:69], off offset:16
	global_load_dwordx4 v[100:103], v[68:69], off
	global_load_dwordx4 v[88:91], v[80:81], off offset:16
	global_load_dwordx4 v[96:99], v[80:81], off
	global_load_dwordx4 v[76:79], v[68:69], off offset:528
	global_load_dwordx4 v[84:87], v[68:69], off offset:512
	s_nop 0
	global_load_dwordx4 v[68:71], v[80:81], off offset:528
	s_nop 0
	global_load_dwordx4 v[80:83], v[80:81], off offset:512
	s_nop 0
	global_load_dwordx4 v[216:219], v[164:165], off offset:16
	global_load_dwordx4 v[220:223], v[164:165], off
	global_load_dwordx4 v[224:227], v[164:165], off offset:528
	global_load_dwordx4 v[228:231], v[164:165], off offset:512
	v_or_b32_e32 v208, 16, v190
	v_ashrrev_i32_e32 v209, 31, v208
	v_lshlrev_b64 v[210:211], 13, v[208:209]
	v_lshl_add_u64 v[168:169], v[206:207], 0, v[210:211]
	global_load_dwordx4 v[172:175], v[168:169], off offset:16
	global_load_dwordx4 v[176:179], v[168:169], off
	global_load_dwordx4 v[164:167], v[168:169], off offset:528
	s_nop 0
	global_load_dwordx4 v[168:171], v[168:169], off offset:512
	v_lshl_add_u64 v[200:201], s[82:83], 0, v[200:201]
	v_lshl_add_u64 v[198:199], v[200:201], 0, v[198:199]
	v_mov_b64_e32 v[200:201], s[4:5]
	v_mad_i64_i32 v[200:201], s[6:7], v190, s66, v[200:201]
	v_lshl_add_u64 v[200:201], v[188:189], 1, v[200:201]
	s_lshl_b32 s44, s12, 2
	s_ashr_i32 s45, s44, 31
	s_waitcnt vmcnt(0)
	v_pk_add_f32 v[156:157], v[156:157], v[92:93]
	v_pk_add_f32 v[162:163], v[162:163], v[102:103]
	v_pk_add_f32 v[160:161], v[160:161], v[100:101]
	v_pk_add_f32 v[158:159], v[158:159], v[94:95]
	v_pk_add_f32 v[148:149], v[148:149], v[76:77]
	v_pk_fma_f32 v[156:157], v[88:89], v[156:157], v[216:217]
	v_pk_fma_f32 v[162:163], v[98:99], v[162:163], v[222:223]
	v_pk_fma_f32 v[160:161], v[96:97], v[160:161], v[220:221]
	v_mul_f32_e32 v216, v163, v163
	v_mul_f32_e32 v215, v161, v161
	v_fmac_f32_e32 v215, v160, v160
	v_fmac_f32_e32 v216, v162, v162
	v_pk_add_f32 v[154:155], v[154:155], v[86:87]
	v_pk_add_f32 v[152:153], v[152:153], v[84:85]
	v_add_f32_e32 v215, v215, v216
	v_mul_f32_e32 v216, v157, v157
	v_pk_fma_f32 v[154:155], v[82:83], v[154:155], v[230:231]
	v_pk_fma_f32 v[152:153], v[80:81], v[152:153], v[228:229]
	v_pk_fma_f32 v[158:159], v[90:91], v[158:159], v[218:219]
	global_store_dwordx4 v[198:199], v[160:163], off
	global_store_dwordx4 v[198:199], v[156:159], off offset:16
	v_fmac_f32_e32 v216, v156, v156
	v_cvt_pk_bf16_f32 v160, v160, v161
	v_cvt_pk_bf16_f32 v161, v162, v163
	v_cvt_pk_bf16_f32 v162, v156, v157
	v_pk_fma_f32 v[148:149], v[68:69], v[148:149], v[224:225]
	v_mul_f32_e32 v156, v153, v153
	v_mul_f32_e32 v157, v155, v155
	v_fmac_f32_e32 v156, v152, v152
	v_fmac_f32_e32 v157, v154, v154
	v_pk_add_f32 v[150:151], v[150:151], v[78:79]
	v_add_f32_e32 v156, v156, v157
	v_mul_f32_e32 v157, v149, v149
	v_cvt_pk_bf16_f32 v163, v158, v159
	global_store_dwordx4 v[200:201], v[160:163], off
	v_pk_fma_f32 v[150:151], v[70:71], v[150:151], v[226:227]
	global_store_dwordx4 v[198:199], v[152:155], off offset:512
	global_store_dwordx4 v[198:199], v[148:151], off offset:528
	v_fmac_f32_e32 v157, v148, v148
	v_cvt_pk_bf16_f32 v152, v152, v153
	v_cvt_pk_bf16_f32 v153, v154, v155
	v_cvt_pk_bf16_f32 v154, v148, v149
	v_add_f32_e32 v215, v215, v216
	v_and_b32_e32 v149, 64, v239
	v_mul_f32_e32 v216, v159, v159
	v_add_f32_e32 v156, v156, v157
	v_mul_f32_e32 v157, v151, v151
	v_xor_b32_e32 v148, 16, v239
	v_add_u32_e32 v149, 64, v149
	v_fmac_f32_e32 v216, v158, v158
	v_fmac_f32_e32 v157, v150, v150
	v_cmp_lt_i32_e32 vcc, v148, v149
	v_add_f32_e32 v215, v216, v215
	v_add_f32_e32 v156, v157, v156
	v_cndmask_b32_e32 v148, v239, v148, vcc
	v_add_f32_e32 v156, v215, v156
	v_cvt_pk_bf16_f32 v155, v150, v151
	global_store_dwordx4 v[200:201], v[152:155], off offset:256
	v_xor_b32_e32 v150, 32, v239
	v_cmp_lt_i32_e32 vcc, v150, v149
	v_lshlrev_b32_e32 v154, 2, v148
	ds_bpermute_b32 v148, v154, v156
	v_cndmask_b32_e32 v149, v239, v150, vcc
	v_lshlrev_b32_e32 v155, 2, v149
	s_waitcnt lgkmcnt(0)
	v_add_f32_e32 v148, v156, v148
	ds_bpermute_b32 v149, v155, v148
	s_and_saveexec_b64 s[50:51], s[38:39]
	s_cbranch_execz .LBB0_172
	v_lshlrev_b64 v[150:151], 7, v[190:191]
	v_lshl_add_u64 v[150:151], s[94:95], 0, v[150:151]
	v_lshl_add_u64 v[150:151], s[44:45], 2, v[150:151]
	s_lshl_b32 s30, s58, 2
	v_lshl_add_u64 v[150:151], v[150:151], 0, s[30:31]
	s_waitcnt lgkmcnt(0)
	v_add_f32_e32 v148, v148, v149
	global_store_dword v[150:151], v148, off

; #define PG8_STAGE(bufoff, gbase, voff) do { _Pragma("unroll") for (int _i = 0; _i < 2; ++_i) \
;         __builtin_amdgcn_global_load_lds((const unsigned*)((const char*)(gbase) + (voff)[_i]), (LAS unsigned*)(lds + (bufoff) + ldsw + _i * 8192), 16, 0, 0); } while (0)
; #define PG8_LDA(dst, b, h) do { _Pragma("unroll") for (int m = 0; m < 4; ++m) _Pragma("unroll") for (int k = 0; k < 2; ++k) dst[m][k] = *(const LAS bf16x8*)(lds + PG8_SA(b, h) + aoff + m * 2048 + k * 1024); } while (0)
; #define PG8_LDB(dst, b, h) do { _Pragma("unroll") for (int n = 0; n < 2; ++n) _Pragma("unroll") for (int k = 0; k < 2; ++k) dst[n][k] = *(const LAS bf16x8*)(lds + PG8_SB(b, h) + boff + n * 2048 + k * 1024); } while (0)
; #define PG8_MMA(ai, bj, At, Bt) do { __builtin_amdgcn_s_setprio(1); _Pragma("unroll") for (int m = 0; m < 4; ++m) _Pragma("unroll") for (int n = 0; n < 2; ++n) _Pragma("unroll") for (int k = 0; k < 2; ++k) \
;         acc[ai][bj][m][n] = __builtin_amdgcn_mfma_f32_16x16x32_bf16(Bt[n][k], At[m][k], acc[ai][bj][m][n], 0, 0, 0); __builtin_amdgcn_s_setprio(0); } while (0)
; #define PG8_WAIT_V(n) asm volatile("s_waitcnt vmcnt(" #n ")" ::: "memory")
; #define PG8_WAIT_L(n) asm volatile("s_waitcnt lgkmcnt(" #n ")" ::: "memory")
; #define PG8_BAR __builtin_amdgcn_s_barrier()
; #define PG8_SCHED __builtin_amdgcn_sched_barrier(0)
; template <class Epi, bool ALIGN_EPI>
; __device__ __forceinline__ void gemm_phase(LAS unsigned char* lds, const Gemm g, int G, int cid, const Epi& E) {
;     ...
;             const char* a1 = cA + (size_t)(t + 1) * kA;
;             const char* a2 = last ? nA : cA + (size_t)(t + 2) * kA; const char* b2 = last ? nB : cB + (size_t)(t + 2) * kB;
;             const char* a3 = a2 + kA; const char* b3 = b2 + kB;
;             PG8_LDB(B0, 0, 0); PG8_LDB(B1, 0, 1); PG8_SCHED; PG8_LDA(At, 0, 0); PG8_STAGE(PG8_SA(1, 1), a1 + hA, voffA);
;             PG8_WAIT_V(8); PG8_WAIT_L(0); PG8_BAR; PG8_MMA(0, 0, At, B0); PG8_MMA(0, 1, At, B1); PG8_BAR; PG8_SCHED;
;             PG8_LDA(At, 0, 1); PG8_STAGE(PG8_SB(0, 0), b2, voffB); PG8_STAGE(PG8_SB(0, 1), b2 + hB, voffB); PG8_STAGE(PG8_SA(0, 0), a2, voffA);
;             PG8_WAIT_V(8); PG8_WAIT_L(0); PG8_BAR; PG8_MMA(1, 0, At, B0); PG8_MMA(1, 1, At, B1); PG8_BAR; PG8_SCHED;
.LBB0_266:
	s_add_u32 s74, s72, 0x100
	s_addc_u32 s75, s73, 0
	s_and_b64 s[58:59], exec, s[58:59]
	s_cselect_b32 s59, s49, s75
	s_cselect_b32 s58, s48, s74
	s_add_i32 s6, 0, 0x10000
	s_add_i32 s7, 0, 0x14000
	v_add_u32_e32 v108, s6, v190
	v_add_u32_e32 v132, s7, v190
	ds_read_b128 v[88:91], v108
	ds_read_b128 v[100:103], v108 offset:1024
	ds_read_b128 v[104:107], v108 offset:2048
	ds_read_b128 v[108:111], v108 offset:3072
	ds_read_b128 v[112:115], v132
	ds_read_b128 v[120:123], v132 offset:1024
	ds_read_b128 v[124:127], v132 offset:2048
	ds_read_b128 v[132:135], v132 offset:3072
	v_lshl_add_u64 v[198:199], s[72:73], 0, v[178:179]
	s_add_i32 m0, s23, 0xc000
	ds_read_b128 v[164:167], v222
	ds_read_b128 v[168:171], v222 offset:1024
	ds_read_b128 v[182:185], v222 offset:2048
	ds_read_b128 v[224:227], v222 offset:3072
	ds_read_b128 v[228:231], v222 offset:4096
	ds_read_b128 v[232:235], v222 offset:5120
	ds_read_b128 v[244:247], v222 offset:6144
	ds_read_b128 v[248:251], v222 offset:7168
	global_load_lds_dwordx4 v[198:199], off
	v_lshl_add_u64 v[198:199], s[72:73], 0, v[180:181]
	s_add_i32 m0, s23, 0xe000
	s_nop 0
	global_load_lds_dwordx4 v[198:199], off
	s_waitcnt vmcnt(8)
	s_waitcnt lgkmcnt(0)
	s_barrier
	s_setprio 1
	s_waitcnt lgkmcnt(0)
	v_mfma_f32_16x16x32_bf16 v[160:163], v[88:91], v[164:167], v[160:163]
	v_mfma_f32_16x16x32_bf16 v[156:159], v[104:107], v[164:167], v[156:159]
	v_mfma_f32_16x16x32_bf16 v[144:147], v[88:91], v[182:185], v[144:147]
	v_mfma_f32_16x16x32_bf16 v[140:143], v[104:107], v[182:185], v[140:143]
	v_mfma_f32_16x16x32_bf16 v[96:99], v[88:91], v[228:231], v[96:99]
	v_mfma_f32_16x16x32_bf16 v[92:95], v[104:107], v[228:231], v[92:95]
	v_mfma_f32_16x16x32_bf16 v[76:79], v[88:91], v[244:247], v[76:79]
	v_mfma_f32_16x16x32_bf16 v[72:75], v[104:107], v[244:247], v[72:75]
	v_mfma_f32_16x16x32_bf16 v[160:163], v[100:103], v[168:171], v[160:163]
	v_mfma_f32_16x16x32_bf16 v[156:159], v[108:111], v[168:171], v[156:159]
	v_mfma_f32_16x16x32_bf16 v[144:147], v[100:103], v[224:227], v[144:147]
	v_mfma_f32_16x16x32_bf16 v[140:143], v[108:111], v[224:227], v[140:143]
	v_mfma_f32_16x16x32_bf16 v[96:99], v[100:103], v[232:235], v[96:99]
	v_mfma_f32_16x16x32_bf16 v[92:95], v[108:111], v[232:235], v[92:95]
	v_mfma_f32_16x16x32_bf16 v[76:79], v[100:103], v[248:251], v[76:79]
	v_mfma_f32_16x16x32_bf16 v[72:75], v[108:111], v[248:251], v[72:75]
	v_mfma_f32_16x16x32_bf16 v[152:155], v[112:115], v[164:167], v[152:155]
	v_mfma_f32_16x16x32_bf16 v[148:151], v[124:127], v[164:167], v[148:151]
	v_mfma_f32_16x16x32_bf16 v[128:131], v[112:115], v[182:185], v[128:131]
	v_mfma_f32_16x16x32_bf16 v[116:119], v[124:127], v[182:185], v[116:119]
	v_mfma_f32_16x16x32_bf16 v[84:87], v[112:115], v[228:231], v[84:87]
	v_mfma_f32_16x16x32_bf16 v[80:83], v[124:127], v[228:231], v[80:83]
	v_mfma_f32_16x16x32_bf16 v[68:71], v[112:115], v[244:247], v[68:71]
	v_mfma_f32_16x16x32_bf16 v[64:67], v[124:127], v[244:247], v[64:67]
	v_mfma_f32_16x16x32_bf16 v[152:155], v[120:123], v[168:171], v[152:155]
	v_mfma_f32_16x16x32_bf16 v[148:151], v[132:135], v[168:171], v[148:151]
	v_mfma_f32_16x16x32_bf16 v[128:131], v[120:123], v[224:227], v[128:131]
	v_mfma_f32_16x16x32_bf16 v[116:119], v[132:135], v[224:227], v[116:119]
	v_mfma_f32_16x16x32_bf16 v[84:87], v[120:123], v[232:235], v[84:87]
	v_mfma_f32_16x16x32_bf16 v[80:83], v[132:135], v[232:235], v[80:83]
	v_mfma_f32_16x16x32_bf16 v[68:71], v[120:123], v[248:251], v[68:71]
	v_mfma_f32_16x16x32_bf16 v[64:67], v[132:135], v[248:251], v[64:67]
	s_setprio 0
	s_barrier
	s_add_i32 s6, s6, s0
	v_lshl_add_u64 v[198:199], s[56:57], 0, v[172:173]
	s_mov_b32 m0, s6
	ds_read_b128 v[164:167], v222 offset:16384
	ds_read_b128 v[168:171], v222 offset:17408
	ds_read_b128 v[182:185], v222 offset:18432
	ds_read_b128 v[224:227], v222 offset:19456
	ds_read_b128 v[228:231], v222 offset:20480
	ds_read_b128 v[232:235], v222 offset:21504
	ds_read_b128 v[244:247], v222 offset:22528
	ds_read_b128 v[248:251], v222 offset:23552
	global_load_lds_dwordx4 v[198:199], off
	s_add_i32 m0, s6, 0x2000
	s_add_u32 s72, s56, 0x2000
	v_lshl_add_u64 v[198:199], s[56:57], 0, v[176:177]
	s_addc_u32 s73, s57, 0
	s_add_i32 s6, s7, s0
	global_load_lds_dwordx4 v[198:199], off
	v_lshl_add_u64 v[198:199], s[72:73], 0, v[172:173]
	s_mov_b32 m0, s6
	v_lshl_add_u64 v[200:201], s[58:59], 0, v[174:175]
	global_load_lds_dwordx4 v[198:199], off
	v_lshl_add_u64 v[198:199], s[72:73], 0, v[176:177]
	s_add_i32 m0, s6, 0x2000
	s_nop 0
	global_load_lds_dwordx4 v[198:199], off
	v_lshl_add_u64 v[198:199], s[58:59], 0, v[136:137]
	s_mov_b32 m0, s23
	s_nop 0
	global_load_lds_dwordx4 v[198:199], off
	s_mov_b32 m0, s24
	s_nop 0
	global_load_lds_dwordx4 v[200:201], off
	s_waitcnt vmcnt(8)
	s_waitcnt lgkmcnt(0)
	s_barrier
; #define PG8_STAGE(bufoff, gbase, voff) do { _Pragma("unroll") for (int _i = 0; _i < 2; ++_i) \
;         __builtin_amdgcn_global_load_lds((const unsigned*)((const char*)(gbase) + (voff)[_i]), (LAS unsigned*)(lds + (bufoff) + ldsw + _i * 8192), 16, 0, 0); } while (0)
; #define PG8_LDA(dst, b, h) do { _Pragma("unroll") for (int m = 0; m < 4; ++m) _Pragma("unroll") for (int k = 0; k < 2; ++k) dst[m][k] = *(const LAS bf16x8*)(lds + PG8_SA(b, h) + aoff + m * 2048 + k * 1024); } while (0)
; #define PG8_LDB(dst, b, h) do { _Pragma("unroll") for (int n = 0; n < 2; ++n) _Pragma("unroll") for (int k = 0; k < 2; ++k) dst[n][k] = *(const LAS bf16x8*)(lds + PG8_SB(b, h) + boff + n * 2048 + k * 1024); } while (0)
; #define PG8_MMA(ai, bj, At, Bt) do { __builtin_amdgcn_s_setprio(1); _Pragma("unroll") for (int m = 0; m < 4; ++m) _Pragma("unroll") for (int n = 0; n < 2; ++n) _Pragma("unroll") for (int k = 0; k < 2; ++k) \
;         acc[ai][bj][m][n] = __builtin_amdgcn_mfma_f32_16x16x32_bf16(Bt[n][k], At[m][k], acc[ai][bj][m][n], 0, 0, 0); __builtin_amdgcn_s_setprio(0); } while (0)
; #define PG8_WAIT_V(n) asm volatile("s_waitcnt vmcnt(" #n ")" ::: "memory")
; #define PG8_WAIT_L(n) asm volatile("s_waitcnt lgkmcnt(" #n ")" ::: "memory")
; #define PG8_BAR __builtin_amdgcn_s_barrier()
; #define PG8_SCHED __builtin_amdgcn_sched_barrier(0)
; template <class Epi, bool ALIGN_EPI>
; __device__ __forceinline__ void gemm_phase(LAS unsigned char* lds, const Gemm g, int G, int cid, const Epi& E) {
;     ...
;             PG8_WAIT_V(8); PG8_WAIT_L(0); PG8_BAR; PG8_MMA(1, 0, At, B0); PG8_MMA(1, 1, At, B1); PG8_BAR; PG8_SCHED;
;             PG8_LDB(B0, 1, 0); PG8_LDB(B1, 1, 1); PG8_SCHED; PG8_LDA(At, 1, 0); PG8_STAGE(PG8_SA(0, 1), a2 + hA, voffA);
;             PG8_WAIT_V(8); PG8_WAIT_L(0); PG8_BAR; PG8_MMA(0, 0, At, B0); PG8_MMA(0, 1, At, B1); PG8_BAR; PG8_SCHED;
	s_setprio 1
	s_waitcnt lgkmcnt(0)
	v_mfma_f32_16x16x32_bf16 v[60:63], v[88:91], v[164:167], v[60:63]
	v_mfma_f32_16x16x32_bf16 v[56:59], v[104:107], v[164:167], v[56:59]
	v_mfma_f32_16x16x32_bf16 v[44:47], v[88:91], v[182:185], v[44:47]
	v_mfma_f32_16x16x32_bf16 v[40:43], v[104:107], v[182:185], v[40:43]
	v_mfma_f32_16x16x32_bf16 v[28:31], v[88:91], v[228:231], v[28:31]
	v_mfma_f32_16x16x32_bf16 v[24:27], v[104:107], v[228:231], v[24:27]
	v_mfma_f32_16x16x32_bf16 v[12:15], v[88:91], v[244:247], v[12:15]
	v_mfma_f32_16x16x32_bf16 v[8:11], v[104:107], v[244:247], v[8:11]
	v_mfma_f32_16x16x32_bf16 v[60:63], v[100:103], v[168:171], v[60:63]
	v_mfma_f32_16x16x32_bf16 v[56:59], v[108:111], v[168:171], v[56:59]
	v_mfma_f32_16x16x32_bf16 v[44:47], v[100:103], v[224:227], v[44:47]
	v_mfma_f32_16x16x32_bf16 v[40:43], v[108:111], v[224:227], v[40:43]
	v_mfma_f32_16x16x32_bf16 v[28:31], v[100:103], v[232:235], v[28:31]
	v_mfma_f32_16x16x32_bf16 v[24:27], v[108:111], v[232:235], v[24:27]
	v_mfma_f32_16x16x32_bf16 v[12:15], v[100:103], v[248:251], v[12:15]
	v_mfma_f32_16x16x32_bf16 v[8:11], v[108:111], v[248:251], v[8:11]
	v_mfma_f32_16x16x32_bf16 v[52:55], v[112:115], v[164:167], v[52:55]
	v_mfma_f32_16x16x32_bf16 v[48:51], v[124:127], v[164:167], v[48:51]
	v_mfma_f32_16x16x32_bf16 v[36:39], v[112:115], v[182:185], v[36:39]
	v_mfma_f32_16x16x32_bf16 v[32:35], v[124:127], v[182:185], v[32:35]
	v_mfma_f32_16x16x32_bf16 v[20:23], v[112:115], v[228:231], v[20:23]
	v_mfma_f32_16x16x32_bf16 v[16:19], v[124:127], v[228:231], v[16:19]
	v_mfma_f32_16x16x32_bf16 v[4:7], v[112:115], v[244:247], v[4:7]
	v_mfma_f32_16x16x32_bf16 v[0:3], v[124:127], v[244:247], v[0:3]
	v_mfma_f32_16x16x32_bf16 v[52:55], v[120:123], v[168:171], v[52:55]
	v_mfma_f32_16x16x32_bf16 v[48:51], v[132:135], v[168:171], v[48:51]
	v_mfma_f32_16x16x32_bf16 v[36:39], v[120:123], v[224:227], v[36:39]
	v_mfma_f32_16x16x32_bf16 v[32:35], v[132:135], v[224:227], v[32:35]
	v_mfma_f32_16x16x32_bf16 v[20:23], v[120:123], v[232:235], v[20:23]
	v_mfma_f32_16x16x32_bf16 v[16:19], v[132:135], v[232:235], v[16:19]
	v_mfma_f32_16x16x32_bf16 v[4:7], v[120:123], v[248:251], v[4:7]
	v_mfma_f32_16x16x32_bf16 v[0:3], v[132:135], v[248:251], v[0:3]
	s_setprio 0
	s_barrier
	s_add_i32 s6, 0, 0x18000
	s_add_i32 s7, 0, 0x1c000
	v_add_u32_e32 v108, s6, v190
	v_add_u32_e32 v132, s7, v190
	ds_read_b128 v[88:91], v108
	ds_read_b128 v[100:103], v108 offset:1024
	ds_read_b128 v[104:107], v108 offset:2048
	ds_read_b128 v[108:111], v108 offset:3072
	ds_read_b128 v[112:115], v132
	ds_read_b128 v[120:123], v132 offset:1024
	ds_read_b128 v[124:127], v132 offset:2048
	ds_read_b128 v[132:135], v132 offset:3072
	s_add_u32 s58, s58, 0x84000
	s_addc_u32 s59, s59, 0
	s_mov_b32 m0, s25
	v_lshl_add_u64 v[242:243], s[58:59], 0, v[136:137]
	ds_read_b128 v[164:167], v222 offset:32768
	ds_read_b128 v[168:171], v222 offset:33792
	ds_read_b128 v[182:185], v222 offset:34816
	ds_read_b128 v[224:227], v222 offset:35840
	ds_read_b128 v[228:231], v222 offset:36864
	ds_read_b128 v[232:235], v222 offset:37888
	ds_read_b128 v[244:247], v222 offset:38912
	ds_read_b128 v[248:251], v222 offset:39936
	global_load_lds_dwordx4 v[242:243], off
	v_lshl_add_u64 v[242:243], s[58:59], 0, v[174:175]
	s_mov_b32 m0, s76
	s_nop 0
	global_load_lds_dwordx4 v[242:243], off
	s_waitcnt vmcnt(8)
	s_waitcnt lgkmcnt(0)
	s_barrier
	s_setprio 1
	s_waitcnt lgkmcnt(0)
	v_mfma_f32_16x16x32_bf16 v[160:163], v[88:91], v[164:167], v[160:163]
	v_mfma_f32_16x16x32_bf16 v[156:159], v[104:107], v[164:167], v[156:159]
	v_mfma_f32_16x16x32_bf16 v[144:147], v[88:91], v[182:185], v[144:147]
	v_mfma_f32_16x16x32_bf16 v[140:143], v[104:107], v[182:185], v[140:143]
	v_mfma_f32_16x16x32_bf16 v[96:99], v[88:91], v[228:231], v[96:99]
	v_mfma_f32_16x16x32_bf16 v[92:95], v[104:107], v[228:231], v[92:95]
	v_mfma_f32_16x16x32_bf16 v[76:79], v[88:91], v[244:247], v[76:79]
	v_mfma_f32_16x16x32_bf16 v[72:75], v[104:107], v[244:247], v[72:75]
	v_mfma_f32_16x16x32_bf16 v[160:163], v[100:103], v[168:171], v[160:163]
	v_mfma_f32_16x16x32_bf16 v[156:159], v[108:111], v[168:171], v[156:159]
	v_mfma_f32_16x16x32_bf16 v[144:147], v[100:103], v[224:227], v[144:147]
	v_mfma_f32_16x16x32_bf16 v[140:143], v[108:111], v[224:227], v[140:143]
	v_mfma_f32_16x16x32_bf16 v[96:99], v[100:103], v[232:235], v[96:99]
	v_mfma_f32_16x16x32_bf16 v[92:95], v[108:111], v[232:235], v[92:95]
	v_mfma_f32_16x16x32_bf16 v[76:79], v[100:103], v[248:251], v[76:79]
	v_mfma_f32_16x16x32_bf16 v[72:75], v[108:111], v[248:251], v[72:75]
	v_mfma_f32_16x16x32_bf16 v[152:155], v[112:115], v[164:167], v[152:155]
	v_mfma_f32_16x16x32_bf16 v[148:151], v[124:127], v[164:167], v[148:151]
	v_mfma_f32_16x16x32_bf16 v[128:131], v[112:115], v[182:185], v[128:131]
	v_mfma_f32_16x16x32_bf16 v[116:119], v[124:127], v[182:185], v[116:119]
	v_mfma_f32_16x16x32_bf16 v[84:87], v[112:115], v[228:231], v[84:87]
	v_mfma_f32_16x16x32_bf16 v[80:83], v[124:127], v[228:231], v[80:83]
	v_mfma_f32_16x16x32_bf16 v[68:71], v[112:115], v[244:247], v[68:71]
	v_mfma_f32_16x16x32_bf16 v[64:67], v[124:127], v[244:247], v[64:67]
	v_mfma_f32_16x16x32_bf16 v[152:155], v[120:123], v[168:171], v[152:155]
	v_mfma_f32_16x16x32_bf16 v[148:151], v[132:135], v[168:171], v[148:151]
	v_mfma_f32_16x16x32_bf16 v[128:131], v[120:123], v[224:227], v[128:131]
	v_mfma_f32_16x16x32_bf16 v[116:119], v[132:135], v[224:227], v[116:119]
	v_mfma_f32_16x16x32_bf16 v[84:87], v[120:123], v[232:235], v[84:87]
	v_mfma_f32_16x16x32_bf16 v[80:83], v[132:135], v[232:235], v[80:83]
	v_mfma_f32_16x16x32_bf16 v[68:71], v[120:123], v[248:251], v[68:71]
	v_mfma_f32_16x16x32_bf16 v[64:67], v[132:135], v[248:251], v[64:67]
	s_setprio 0
	s_barrier
; #define PG8_STAGE(bufoff, gbase, voff) do { _Pragma("unroll") for (int _i = 0; _i < 2; ++_i) \
;         __builtin_amdgcn_global_load_lds((const unsigned*)((const char*)(gbase) + (voff)[_i]), (LAS unsigned*)(lds + (bufoff) + ldsw + _i * 8192), 16, 0, 0); } while (0)
; #define PG8_LDA(dst, b, h) do { _Pragma("unroll") for (int m = 0; m < 4; ++m) _Pragma("unroll") for (int k = 0; k < 2; ++k) dst[m][k] = *(const LAS bf16x8*)(lds + PG8_SA(b, h) + aoff + m * 2048 + k * 1024); } while (0)
; #define PG8_MMA(ai, bj, At, Bt) do { __builtin_amdgcn_s_setprio(1); _Pragma("unroll") for (int m = 0; m < 4; ++m) _Pragma("unroll") for (int n = 0; n < 2; ++n) _Pragma("unroll") for (int k = 0; k < 2; ++k) \
;         acc[ai][bj][m][n] = __builtin_amdgcn_mfma_f32_16x16x32_bf16(Bt[n][k], At[m][k], acc[ai][bj][m][n], 0, 0, 0); __builtin_amdgcn_s_setprio(0); } while (0)
; #define PG8_WAIT_V(n) asm volatile("s_waitcnt vmcnt(" #n ")" ::: "memory")
; #define PG8_WAIT_L(n) asm volatile("s_waitcnt lgkmcnt(" #n ")" ::: "memory")
; #define PG8_BAR __builtin_amdgcn_s_barrier()
; #define PG8_SCHED __builtin_amdgcn_sched_barrier(0)
; template <class Epi, bool ALIGN_EPI>
; __device__ __forceinline__ void gemm_phase(LAS unsigned char* lds, const Gemm g, int G, int cid, const Epi& E) {
;     ...
;         for (int t = 0; t < nt; t += 2) {
;     ...
;             PG8_LDA(At, 1, 1); PG8_STAGE(PG8_SB(1, 0), b3, voffB); PG8_STAGE(PG8_SB(1, 1), b3 + hB, voffB); PG8_STAGE(PG8_SA(1, 0), a3, voffA);
;             PG8_WAIT_V(8); PG8_WAIT_L(0); PG8_BAR; PG8_MMA(1, 0, At, B0); PG8_MMA(1, 1, At, B1); PG8_BAR; PG8_SCHED;
;         }
	s_add_u32 s58, s56, 0xc0000
	s_addc_u32 s59, s57, 0
	s_add_i32 s6, s6, s0
	v_lshl_add_u64 v[242:243], s[58:59], 0, v[172:173]
	s_mov_b32 m0, s6
	ds_read_b128 v[164:167], v222 offset:49152
	ds_read_b128 v[168:171], v222 offset:50176
	ds_read_b128 v[182:185], v222 offset:51200
	ds_read_b128 v[224:227], v222 offset:52224
	ds_read_b128 v[228:231], v222 offset:53248
	ds_read_b128 v[232:235], v222 offset:54272
	ds_read_b128 v[244:247], v222 offset:55296
	ds_read_b128 v[248:251], v222 offset:56320
	global_load_lds_dwordx4 v[242:243], off
	s_add_i32 m0, s6, 0x2000
	s_add_u32 s56, s56, 0xc2000
	v_lshl_add_u64 v[242:243], s[58:59], 0, v[176:177]
	s_addc_u32 s57, s57, 0
	s_add_i32 s6, s7, s0
	global_load_lds_dwordx4 v[242:243], off
	v_lshl_add_u64 v[242:243], s[56:57], 0, v[172:173]
	s_mov_b32 m0, s6
	v_lshl_add_u64 v[198:199], v[198:199], 0, s[36:37]
	global_load_lds_dwordx4 v[242:243], off
	v_lshl_add_u64 v[242:243], s[56:57], 0, v[176:177]
	s_add_i32 m0, s6, 0x2000
	s_nop 0
	global_load_lds_dwordx4 v[242:243], off
	s_mov_b32 m0, s78
	s_nop 0
	global_load_lds_dwordx4 v[198:199], off
	v_lshl_add_u64 v[198:199], v[200:201], 0, s[36:37]
	s_mov_b32 m0, s79
	s_nop 0
	global_load_lds_dwordx4 v[198:199], off
	s_waitcnt vmcnt(8)
	s_waitcnt lgkmcnt(0)
	s_barrier
	s_setprio 1
	s_waitcnt lgkmcnt(0)
	v_mfma_f32_16x16x32_bf16 v[60:63], v[88:91], v[164:167], v[60:63]
	v_mfma_f32_16x16x32_bf16 v[56:59], v[104:107], v[164:167], v[56:59]
	v_mfma_f32_16x16x32_bf16 v[44:47], v[88:91], v[182:185], v[44:47]
	v_mfma_f32_16x16x32_bf16 v[40:43], v[104:107], v[182:185], v[40:43]
	v_mfma_f32_16x16x32_bf16 v[28:31], v[88:91], v[228:231], v[28:31]
	v_mfma_f32_16x16x32_bf16 v[24:27], v[104:107], v[228:231], v[24:27]
	v_mfma_f32_16x16x32_bf16 v[12:15], v[88:91], v[244:247], v[12:15]
	v_mfma_f32_16x16x32_bf16 v[8:11], v[104:107], v[244:247], v[8:11]
	v_mfma_f32_16x16x32_bf16 v[60:63], v[100:103], v[168:171], v[60:63]
	v_mfma_f32_16x16x32_bf16 v[56:59], v[108:111], v[168:171], v[56:59]
	v_mfma_f32_16x16x32_bf16 v[44:47], v[100:103], v[224:227], v[44:47]
	v_mfma_f32_16x16x32_bf16 v[40:43], v[108:111], v[224:227], v[40:43]
	v_mfma_f32_16x16x32_bf16 v[28:31], v[100:103], v[232:235], v[28:31]
	v_mfma_f32_16x16x32_bf16 v[24:27], v[108:111], v[232:235], v[24:27]
	v_mfma_f32_16x16x32_bf16 v[12:15], v[100:103], v[248:251], v[12:15]
	v_mfma_f32_16x16x32_bf16 v[8:11], v[108:111], v[248:251], v[8:11]
	v_mfma_f32_16x16x32_bf16 v[52:55], v[112:115], v[164:167], v[52:55]
	v_mfma_f32_16x16x32_bf16 v[48:51], v[124:127], v[164:167], v[48:51]
	v_mfma_f32_16x16x32_bf16 v[36:39], v[112:115], v[182:185], v[36:39]
	v_mfma_f32_16x16x32_bf16 v[32:35], v[124:127], v[182:185], v[32:35]
	v_mfma_f32_16x16x32_bf16 v[20:23], v[112:115], v[228:231], v[20:23]
	v_mfma_f32_16x16x32_bf16 v[16:19], v[124:127], v[228:231], v[16:19]
	v_mfma_f32_16x16x32_bf16 v[4:7], v[112:115], v[244:247], v[4:7]
	v_mfma_f32_16x16x32_bf16 v[0:3], v[124:127], v[244:247], v[0:3]
	v_mfma_f32_16x16x32_bf16 v[52:55], v[120:123], v[168:171], v[52:55]
	v_mfma_f32_16x16x32_bf16 v[48:51], v[132:135], v[168:171], v[48:51]
	v_mfma_f32_16x16x32_bf16 v[36:39], v[120:123], v[224:227], v[36:39]
	v_mfma_f32_16x16x32_bf16 v[32:35], v[132:135], v[224:227], v[32:35]
	v_mfma_f32_16x16x32_bf16 v[20:23], v[120:123], v[232:235], v[20:23]
	v_mfma_f32_16x16x32_bf16 v[16:19], v[132:135], v[232:235], v[16:19]
	v_mfma_f32_16x16x32_bf16 v[4:7], v[120:123], v[248:251], v[4:7]
	v_mfma_f32_16x16x32_bf16 v[0:3], v[132:135], v[248:251], v[0:3]
	s_setprio 0
	s_barrier
	s_add_i32 s30, s30, 2
	s_add_u32 s54, s54, 0x180000
	s_addc_u32 s55, s55, 0
	s_cmp_gt_u32 s30, 29
	s_mov_b64 s[72:73], s[74:75]
	s_cbranch_scc1 .LBB0_269

; #define PG8_STAGE(bufoff, gbase, voff) do { _Pragma("unroll") for (int _i = 0; _i < 2; ++_i) \
;         __builtin_amdgcn_global_load_lds((const unsigned*)((const char*)(gbase) + (voff)[_i]), (LAS unsigned*)(lds + (bufoff) + ldsw + _i * 8192), 16, 0, 0); } while (0)
; #define PG8_LDA(dst, b, h) do { _Pragma("unroll") for (int m = 0; m < 4; ++m) _Pragma("unroll") for (int k = 0; k < 2; ++k) dst[m][k] = *(const LAS bf16x8*)(lds + PG8_SA(b, h) + aoff + m * 2048 + k * 1024); } while (0)
; #define PG8_LDB(dst, b, h) do { _Pragma("unroll") for (int n = 0; n < 2; ++n) _Pragma("unroll") for (int k = 0; k < 2; ++k) dst[n][k] = *(const LAS bf16x8*)(lds + PG8_SB(b, h) + boff + n * 2048 + k * 1024); } while (0)
; #define PG8_MMA(ai, bj, At, Bt) do { __builtin_amdgcn_s_setprio(1); _Pragma("unroll") for (int m = 0; m < 4; ++m) _Pragma("unroll") for (int n = 0; n < 2; ++n) _Pragma("unroll") for (int k = 0; k < 2; ++k) \
;         acc[ai][bj][m][n] = __builtin_amdgcn_mfma_f32_16x16x32_bf16(Bt[n][k], At[m][k], acc[ai][bj][m][n], 0, 0, 0); __builtin_amdgcn_s_setprio(0); } while (0)
; #define PG8_WAIT_V(n) asm volatile("s_waitcnt vmcnt(" #n ")" ::: "memory")
; #define PG8_WAIT_L(n) asm volatile("s_waitcnt lgkmcnt(" #n ")" ::: "memory")
; #define PG8_BAR __builtin_amdgcn_s_barrier()
; #define PG8_SCHED __builtin_amdgcn_sched_barrier(0)
; template <class Epi, bool ALIGN_EPI>
; __device__ __forceinline__ void gemm_phase(LAS unsigned char* lds, const Gemm g, int G, int cid, const Epi& E) {
;     ...
;         for (int t = 0; t < nt; t += 2) {
;             const bool last = (t == nt - 2);
;             const char* a1 = cA + (size_t)(t + 1) * kA;
;             const char* a2 = last ? nA : cA + (size_t)(t + 2) * kA; const char* b2 = last ? nB : cB + (size_t)(t + 2) * kB;
;             const char* a3 = a2 + kA; const char* b3 = b2 + kB;
;             PG8_LDB(B0, 0, 0); PG8_LDB(B1, 0, 1); PG8_SCHED; PG8_LDA(At, 0, 0); PG8_STAGE(PG8_SA(1, 1), a1 + hA, voffA);
;             PG8_WAIT_V(8); PG8_WAIT_L(0); PG8_BAR; PG8_MMA(0, 0, At, B0); PG8_MMA(0, 1, At, B1); PG8_BAR; PG8_SCHED;
;             PG8_LDA(At, 0, 1); PG8_STAGE(PG8_SB(0, 0), b2, voffB); PG8_STAGE(PG8_SB(0, 1), b2 + hB, voffB); PG8_STAGE(PG8_SA(0, 0), a2, voffA);
;             PG8_WAIT_V(8); PG8_WAIT_L(0); PG8_BAR; PG8_MMA(1, 0, At, B0); PG8_MMA(1, 1, At, B1); PG8_BAR; PG8_SCHED;
.LBB0_727:
	s_add_u32 s42, s46, 0x100
	s_addc_u32 s43, s47, 0
	s_add_i32 s6, 0, 0x10000
	s_cmp_eq_u32 s77, 28
	s_cselect_b32 s51, s29, s43
	s_cselect_b32 s50, s28, s42
	s_cselect_b32 s49, s30, s76
	s_cselect_b32 s48, s74, s75
	s_add_i32 s7, 0, 0x14000
	v_add_u32_e32 v132, s6, v220
	v_add_u32_e32 v160, s7, v220
	ds_read_b128 v[112:115], v132
	ds_read_b128 v[116:119], v132 offset:1024
	ds_read_b128 v[128:131], v132 offset:2048
	ds_read_b128 v[132:135], v132 offset:3072
	ds_read_b128 v[140:143], v160
	ds_read_b128 v[144:147], v160 offset:1024
	ds_read_b128 v[156:159], v160 offset:2048
	ds_read_b128 v[160:163], v160 offset:3072
	v_lshl_add_u64 v[198:199], s[46:47], 0, v[184:185]
	s_add_i32 m0, s52, 0xc000
	ds_read_b128 v[164:167], v222
	ds_read_b128 v[168:171], v222 offset:1024
	ds_read_b128 v[172:175], v222 offset:2048
	ds_read_b128 v[176:179], v222 offset:3072
	ds_read_b128 v[188:191], v222 offset:4096
	ds_read_b128 v[206:209], v222 offset:5120
	ds_read_b128 v[210:213], v222 offset:6144
	ds_read_b128 v[214:217], v222 offset:7168
	global_load_lds_dwordx4 v[198:199], off
	v_lshl_add_u64 v[198:199], s[46:47], 0, v[186:187]
	s_add_i32 m0, s52, 0xe000
	s_nop 0
	global_load_lds_dwordx4 v[198:199], off
	s_add_i32 vcc_lo, s77, 2
	s_lshl_b32 vcc_lo, vcc_lo, 16
	s_lshl_b32 vcc_hi, s13, 21
	s_add_i32 vcc_lo, vcc_lo, vcc_hi
	s_lshl_b32 vcc_hi, s25, 4
	s_add_i32 vcc_lo, vcc_lo, vcc_hi
	s_lshl_b32 vcc_hi, s12, 10
	s_add_i32 vcc_lo, vcc_lo, vcc_hi
	s_add_u32 vcc_lo, s22, vcc_lo
	s_addc_u32 vcc_hi, s23, 0
	s_mov_b32 m0, 0x22c00
	s_nop 0
	global_load_lds_dwordx4 v224, vcc
	s_waitcnt vmcnt(9)
	s_waitcnt lgkmcnt(0)
	s_barrier
	s_setprio 1
	s_waitcnt lgkmcnt(0)
	v_mfma_f32_16x16x32_bf16 v[152:155], v[112:115], v[164:167], v[152:155]
	v_mfma_f32_16x16x32_bf16 v[148:151], v[128:131], v[164:167], v[148:151]
	v_mfma_f32_16x16x32_bf16 v[108:111], v[112:115], v[172:175], v[108:111]
	v_mfma_f32_16x16x32_bf16 v[104:107], v[128:131], v[172:175], v[104:107]
	v_mfma_f32_16x16x32_bf16 v[92:95], v[112:115], v[188:191], v[92:95]
	v_mfma_f32_16x16x32_bf16 v[88:91], v[128:131], v[188:191], v[88:91]
	v_mfma_f32_16x16x32_bf16 v[76:79], v[112:115], v[210:213], v[76:79]
	v_mfma_f32_16x16x32_bf16 v[72:75], v[128:131], v[210:213], v[72:75]
	v_mfma_f32_16x16x32_bf16 v[152:155], v[116:119], v[168:171], v[152:155]
	v_mfma_f32_16x16x32_bf16 v[148:151], v[132:135], v[168:171], v[148:151]
	v_mfma_f32_16x16x32_bf16 v[108:111], v[116:119], v[176:179], v[108:111]
	v_mfma_f32_16x16x32_bf16 v[104:107], v[132:135], v[176:179], v[104:107]
	v_mfma_f32_16x16x32_bf16 v[92:95], v[116:119], v[206:209], v[92:95]
	v_mfma_f32_16x16x32_bf16 v[88:91], v[132:135], v[206:209], v[88:91]
	v_mfma_f32_16x16x32_bf16 v[76:79], v[116:119], v[214:217], v[76:79]
	v_mfma_f32_16x16x32_bf16 v[72:75], v[132:135], v[214:217], v[72:75]
	v_mfma_f32_16x16x32_bf16 v[124:127], v[140:143], v[164:167], v[124:127]
	v_mfma_f32_16x16x32_bf16 v[120:123], v[156:159], v[164:167], v[120:123]
	v_mfma_f32_16x16x32_bf16 v[100:103], v[140:143], v[172:175], v[100:103]
	v_mfma_f32_16x16x32_bf16 v[96:99], v[156:159], v[172:175], v[96:99]
	v_mfma_f32_16x16x32_bf16 v[84:87], v[140:143], v[188:191], v[84:87]
	v_mfma_f32_16x16x32_bf16 v[80:83], v[156:159], v[188:191], v[80:83]
	v_mfma_f32_16x16x32_bf16 v[68:71], v[140:143], v[210:213], v[68:71]
	v_mfma_f32_16x16x32_bf16 v[64:67], v[156:159], v[210:213], v[64:67]
	v_mfma_f32_16x16x32_bf16 v[124:127], v[144:147], v[168:171], v[124:127]
	v_mfma_f32_16x16x32_bf16 v[120:123], v[160:163], v[168:171], v[120:123]
	v_mfma_f32_16x16x32_bf16 v[100:103], v[144:147], v[176:179], v[100:103]
	v_mfma_f32_16x16x32_bf16 v[96:99], v[160:163], v[176:179], v[96:99]
	v_mfma_f32_16x16x32_bf16 v[84:87], v[144:147], v[206:209], v[84:87]
	v_mfma_f32_16x16x32_bf16 v[80:83], v[160:163], v[206:209], v[80:83]
	v_mfma_f32_16x16x32_bf16 v[68:71], v[144:147], v[214:217], v[68:71]
	v_mfma_f32_16x16x32_bf16 v[64:67], v[160:163], v[214:217], v[64:67]
	s_setprio 0
	s_barrier
	s_add_i32 s6, s6, s25
	v_lshl_add_u64 v[198:199], s[48:49], 0, v[138:139]
	s_mov_b32 m0, s6
	ds_read_b128 v[164:167], v222 offset:16384
	ds_read_b128 v[168:171], v222 offset:17408
	ds_read_b128 v[172:175], v222 offset:18432
	ds_read_b128 v[176:179], v222 offset:19456
	ds_read_b128 v[188:191], v222 offset:20480
	ds_read_b128 v[206:209], v222 offset:21504
	ds_read_b128 v[210:213], v222 offset:22528
	ds_read_b128 v[214:217], v222 offset:23552
	global_load_lds_dwordx4 v[198:199], off
	s_add_i32 m0, s6, 0x2000
	s_add_u32 s46, s48, 0x2000
	v_lshl_add_u64 v[198:199], s[48:49], 0, v[136:137]
	s_addc_u32 s47, s49, 0
	s_add_i32 s6, s7, s25
	global_load_lds_dwordx4 v[198:199], off
	v_lshl_add_u64 v[198:199], s[46:47], 0, v[138:139]
	s_mov_b32 m0, s6
	v_lshl_add_u64 v[200:201], s[50:51], 0, v[180:181]
	global_load_lds_dwordx4 v[198:199], off
	v_lshl_add_u64 v[198:199], s[46:47], 0, v[136:137]
	s_add_i32 m0, s6, 0x2000
	s_nop 0
	global_load_lds_dwordx4 v[198:199], off
	v_lshl_add_u64 v[198:199], s[50:51], 0, v[182:183]
	s_mov_b32 m0, s52
	s_nop 0
	global_load_lds_dwordx4 v[198:199], off
	s_mov_b32 m0, s53
	s_nop 0
	global_load_lds_dwordx4 v[200:201], off
	s_waitcnt vmcnt(9)
	s_waitcnt lgkmcnt(0)
	s_barrier
; #define PG8_STAGE(bufoff, gbase, voff) do { _Pragma("unroll") for (int _i = 0; _i < 2; ++_i) \
;         __builtin_amdgcn_global_load_lds((const unsigned*)((const char*)(gbase) + (voff)[_i]), (LAS unsigned*)(lds + (bufoff) + ldsw + _i * 8192), 16, 0, 0); } while (0)
; #define PG8_LDA(dst, b, h) do { _Pragma("unroll") for (int m = 0; m < 4; ++m) _Pragma("unroll") for (int k = 0; k < 2; ++k) dst[m][k] = *(const LAS bf16x8*)(lds + PG8_SA(b, h) + aoff + m * 2048 + k * 1024); } while (0)
; #define PG8_LDB(dst, b, h) do { _Pragma("unroll") for (int n = 0; n < 2; ++n) _Pragma("unroll") for (int k = 0; k < 2; ++k) dst[n][k] = *(const LAS bf16x8*)(lds + PG8_SB(b, h) + boff + n * 2048 + k * 1024); } while (0)
; #define PG8_MMA(ai, bj, At, Bt) do { __builtin_amdgcn_s_setprio(1); _Pragma("unroll") for (int m = 0; m < 4; ++m) _Pragma("unroll") for (int n = 0; n < 2; ++n) _Pragma("unroll") for (int k = 0; k < 2; ++k) \
;         acc[ai][bj][m][n] = __builtin_amdgcn_mfma_f32_16x16x32_bf16(Bt[n][k], At[m][k], acc[ai][bj][m][n], 0, 0, 0); __builtin_amdgcn_s_setprio(0); } while (0)
; #define PG8_WAIT_V(n) asm volatile("s_waitcnt vmcnt(" #n ")" ::: "memory")
; #define PG8_WAIT_L(n) asm volatile("s_waitcnt lgkmcnt(" #n ")" ::: "memory")
; #define PG8_BAR __builtin_amdgcn_s_barrier()
; #define PG8_SCHED __builtin_amdgcn_sched_barrier(0)
; template <class Epi, bool ALIGN_EPI>
; __device__ __forceinline__ void gemm_phase(LAS unsigned char* lds, const Gemm g, int G, int cid, const Epi& E) {
;     ...
;             PG8_WAIT_V(8); PG8_WAIT_L(0); PG8_BAR; PG8_MMA(1, 0, At, B0); PG8_MMA(1, 1, At, B1); PG8_BAR; PG8_SCHED;
;             PG8_LDB(B0, 1, 0); PG8_LDB(B1, 1, 1); PG8_SCHED; PG8_LDA(At, 1, 0); PG8_STAGE(PG8_SA(0, 1), a2 + hA, voffA);
;             PG8_WAIT_V(8); PG8_WAIT_L(0); PG8_BAR; PG8_MMA(0, 0, At, B0); PG8_MMA(0, 1, At, B1); PG8_BAR; PG8_SCHED;
	s_setprio 1
	s_waitcnt lgkmcnt(0)
	v_mfma_f32_16x16x32_bf16 v[60:63], v[112:115], v[164:167], v[60:63]
	v_mfma_f32_16x16x32_bf16 v[56:59], v[128:131], v[164:167], v[56:59]
	v_mfma_f32_16x16x32_bf16 v[44:47], v[112:115], v[172:175], v[44:47]
	v_mfma_f32_16x16x32_bf16 v[40:43], v[128:131], v[172:175], v[40:43]
	v_mfma_f32_16x16x32_bf16 v[28:31], v[112:115], v[188:191], v[28:31]
	v_mfma_f32_16x16x32_bf16 v[24:27], v[128:131], v[188:191], v[24:27]
	v_mfma_f32_16x16x32_bf16 v[12:15], v[112:115], v[210:213], v[12:15]
	v_mfma_f32_16x16x32_bf16 v[8:11], v[128:131], v[210:213], v[8:11]
	v_mfma_f32_16x16x32_bf16 v[60:63], v[116:119], v[168:171], v[60:63]
	v_mfma_f32_16x16x32_bf16 v[56:59], v[132:135], v[168:171], v[56:59]
	v_mfma_f32_16x16x32_bf16 v[44:47], v[116:119], v[176:179], v[44:47]
	v_mfma_f32_16x16x32_bf16 v[40:43], v[132:135], v[176:179], v[40:43]
	v_mfma_f32_16x16x32_bf16 v[28:31], v[116:119], v[206:209], v[28:31]
	v_mfma_f32_16x16x32_bf16 v[24:27], v[132:135], v[206:209], v[24:27]
	v_mfma_f32_16x16x32_bf16 v[12:15], v[116:119], v[214:217], v[12:15]
	v_mfma_f32_16x16x32_bf16 v[8:11], v[132:135], v[214:217], v[8:11]
	v_mfma_f32_16x16x32_bf16 v[52:55], v[140:143], v[164:167], v[52:55]
	v_mfma_f32_16x16x32_bf16 v[48:51], v[156:159], v[164:167], v[48:51]
	v_mfma_f32_16x16x32_bf16 v[36:39], v[140:143], v[172:175], v[36:39]
	v_mfma_f32_16x16x32_bf16 v[32:35], v[156:159], v[172:175], v[32:35]
	v_mfma_f32_16x16x32_bf16 v[20:23], v[140:143], v[188:191], v[20:23]
	v_mfma_f32_16x16x32_bf16 v[16:19], v[156:159], v[188:191], v[16:19]
	v_mfma_f32_16x16x32_bf16 v[4:7], v[140:143], v[210:213], v[4:7]
	v_mfma_f32_16x16x32_bf16 v[0:3], v[156:159], v[210:213], v[0:3]
	v_mfma_f32_16x16x32_bf16 v[52:55], v[144:147], v[168:171], v[52:55]
	v_mfma_f32_16x16x32_bf16 v[48:51], v[160:163], v[168:171], v[48:51]
	v_mfma_f32_16x16x32_bf16 v[36:39], v[144:147], v[176:179], v[36:39]
	v_mfma_f32_16x16x32_bf16 v[32:35], v[160:163], v[176:179], v[32:35]
	v_mfma_f32_16x16x32_bf16 v[20:23], v[144:147], v[206:209], v[20:23]
	v_mfma_f32_16x16x32_bf16 v[16:19], v[160:163], v[206:209], v[16:19]
	v_mfma_f32_16x16x32_bf16 v[4:7], v[144:147], v[214:217], v[4:7]
	v_mfma_f32_16x16x32_bf16 v[0:3], v[160:163], v[214:217], v[0:3]
	s_setprio 0
	s_barrier
	s_add_i32 s6, 0, 0x18000
	s_add_i32 s7, 0, 0x1c000
	v_add_u32_e32 v132, s6, v220
	v_add_u32_e32 v160, s7, v220
	ds_read_b128 v[112:115], v132
	ds_read_b128 v[116:119], v132 offset:1024
	ds_read_b128 v[128:131], v132 offset:2048
	ds_read_b128 v[132:135], v132 offset:3072
	ds_read_b128 v[140:143], v160
	ds_read_b128 v[144:147], v160 offset:1024
	ds_read_b128 v[156:159], v160 offset:2048
	ds_read_b128 v[160:163], v160 offset:3072
	s_add_u32 s46, s50, 0x84000
	s_addc_u32 s47, s51, 0
	s_mov_b32 m0, s54
	v_lshl_add_u64 v[218:219], s[46:47], 0, v[182:183]
	ds_read_b128 v[164:167], v222 offset:32768
	ds_read_b128 v[168:171], v222 offset:33792
	ds_read_b128 v[172:175], v222 offset:34816
	ds_read_b128 v[176:179], v222 offset:35840
	ds_read_b128 v[188:191], v222 offset:36864
	ds_read_b128 v[206:209], v222 offset:37888
	ds_read_b128 v[210:213], v222 offset:38912
	ds_read_b128 v[214:217], v222 offset:39936
	global_load_lds_dwordx4 v[218:219], off
	v_lshl_add_u64 v[218:219], s[46:47], 0, v[180:181]
	s_mov_b32 m0, s55
	s_nop 0
	global_load_lds_dwordx4 v[218:219], off
	s_add_u32 vcc_lo, vcc_lo, 0x2000
	s_addc_u32 vcc_hi, vcc_hi, 0
	s_mov_b32 m0, 0x22c00
	s_nop 0
	global_load_lds_dwordx4 v224, vcc
	s_waitcnt vmcnt(9)
	s_waitcnt lgkmcnt(0)
	s_barrier
	s_setprio 1
	s_waitcnt lgkmcnt(0)
	v_mfma_f32_16x16x32_bf16 v[152:155], v[112:115], v[164:167], v[152:155]
	v_mfma_f32_16x16x32_bf16 v[148:151], v[128:131], v[164:167], v[148:151]
	v_mfma_f32_16x16x32_bf16 v[108:111], v[112:115], v[172:175], v[108:111]
	v_mfma_f32_16x16x32_bf16 v[104:107], v[128:131], v[172:175], v[104:107]
	v_mfma_f32_16x16x32_bf16 v[92:95], v[112:115], v[188:191], v[92:95]
	v_mfma_f32_16x16x32_bf16 v[88:91], v[128:131], v[188:191], v[88:91]
	v_mfma_f32_16x16x32_bf16 v[76:79], v[112:115], v[210:213], v[76:79]
	v_mfma_f32_16x16x32_bf16 v[72:75], v[128:131], v[210:213], v[72:75]
	v_mfma_f32_16x16x32_bf16 v[152:155], v[116:119], v[168:171], v[152:155]
	v_mfma_f32_16x16x32_bf16 v[148:151], v[132:135], v[168:171], v[148:151]
	v_mfma_f32_16x16x32_bf16 v[108:111], v[116:119], v[176:179], v[108:111]
	v_mfma_f32_16x16x32_bf16 v[104:107], v[132:135], v[176:179], v[104:107]
	v_mfma_f32_16x16x32_bf16 v[92:95], v[116:119], v[206:209], v[92:95]
	v_mfma_f32_16x16x32_bf16 v[88:91], v[132:135], v[206:209], v[88:91]
	v_mfma_f32_16x16x32_bf16 v[76:79], v[116:119], v[214:217], v[76:79]
	v_mfma_f32_16x16x32_bf16 v[72:75], v[132:135], v[214:217], v[72:75]
	v_mfma_f32_16x16x32_bf16 v[124:127], v[140:143], v[164:167], v[124:127]
	v_mfma_f32_16x16x32_bf16 v[120:123], v[156:159], v[164:167], v[120:123]
	v_mfma_f32_16x16x32_bf16 v[100:103], v[140:143], v[172:175], v[100:103]
	v_mfma_f32_16x16x32_bf16 v[96:99], v[156:159], v[172:175], v[96:99]
	v_mfma_f32_16x16x32_bf16 v[84:87], v[140:143], v[188:191], v[84:87]
	v_mfma_f32_16x16x32_bf16 v[80:83], v[156:159], v[188:191], v[80:83]
	v_mfma_f32_16x16x32_bf16 v[68:71], v[140:143], v[210:213], v[68:71]
	v_mfma_f32_16x16x32_bf16 v[64:67], v[156:159], v[210:213], v[64:67]
	v_mfma_f32_16x16x32_bf16 v[124:127], v[144:147], v[168:171], v[124:127]
	v_mfma_f32_16x16x32_bf16 v[120:123], v[160:163], v[168:171], v[120:123]
	v_mfma_f32_16x16x32_bf16 v[100:103], v[144:147], v[176:179], v[100:103]
	v_mfma_f32_16x16x32_bf16 v[96:99], v[160:163], v[176:179], v[96:99]
	v_mfma_f32_16x16x32_bf16 v[84:87], v[144:147], v[206:209], v[84:87]
	v_mfma_f32_16x16x32_bf16 v[80:83], v[160:163], v[206:209], v[80:83]
	v_mfma_f32_16x16x32_bf16 v[68:71], v[144:147], v[214:217], v[68:71]
	v_mfma_f32_16x16x32_bf16 v[64:67], v[160:163], v[214:217], v[64:67]
	s_setprio 0
	s_barrier
; #define PG8_STAGE(bufoff, gbase, voff) do { _Pragma("unroll") for (int _i = 0; _i < 2; ++_i) \
;         __builtin_amdgcn_global_load_lds((const unsigned*)((const char*)(gbase) + (voff)[_i]), (LAS unsigned*)(lds + (bufoff) + ldsw + _i * 8192), 16, 0, 0); } while (0)
; #define PG8_LDA(dst, b, h) do { _Pragma("unroll") for (int m = 0; m < 4; ++m) _Pragma("unroll") for (int k = 0; k < 2; ++k) dst[m][k] = *(const LAS bf16x8*)(lds + PG8_SA(b, h) + aoff + m * 2048 + k * 1024); } while (0)
; #define PG8_MMA(ai, bj, At, Bt) do { __builtin_amdgcn_s_setprio(1); _Pragma("unroll") for (int m = 0; m < 4; ++m) _Pragma("unroll") for (int n = 0; n < 2; ++n) _Pragma("unroll") for (int k = 0; k < 2; ++k) \
;         acc[ai][bj][m][n] = __builtin_amdgcn_mfma_f32_16x16x32_bf16(Bt[n][k], At[m][k], acc[ai][bj][m][n], 0, 0, 0); __builtin_amdgcn_s_setprio(0); } while (0)
; #define PG8_WAIT_V(n) asm volatile("s_waitcnt vmcnt(" #n ")" ::: "memory")
; #define PG8_WAIT_L(n) asm volatile("s_waitcnt lgkmcnt(" #n ")" ::: "memory")
; #define PG8_BAR __builtin_amdgcn_s_barrier()
; #define PG8_SCHED __builtin_amdgcn_sched_barrier(0)
; template <class Epi, bool ALIGN_EPI>
; __device__ __forceinline__ void gemm_phase(LAS unsigned char* lds, const Gemm g, int G, int cid, const Epi& E) {
;     ...
;             PG8_WAIT_V(8); PG8_WAIT_L(0); PG8_BAR; PG8_MMA(0, 0, At, B0); PG8_MMA(0, 1, At, B1); PG8_BAR; PG8_SCHED;
;             PG8_LDA(At, 1, 1); PG8_STAGE(PG8_SB(1, 0), b3, voffB); PG8_STAGE(PG8_SB(1, 1), b3 + hB, voffB); PG8_STAGE(PG8_SA(1, 0), a3, voffA);
;             PG8_WAIT_V(8); PG8_WAIT_L(0); PG8_BAR; PG8_MMA(1, 0, At, B0); PG8_MMA(1, 1, At, B1); PG8_BAR; PG8_SCHED;
;         }
	s_add_u32 s46, s48, 0x40000
	s_addc_u32 s47, s49, 0
	s_add_i32 s6, s6, s25
	v_lshl_add_u64 v[218:219], s[46:47], 0, v[138:139]
	s_mov_b32 m0, s6
	ds_read_b128 v[164:167], v222 offset:49152
	ds_read_b128 v[168:171], v222 offset:50176
	ds_read_b128 v[172:175], v222 offset:51200
	ds_read_b128 v[176:179], v222 offset:52224
	ds_read_b128 v[188:191], v222 offset:53248
	ds_read_b128 v[206:209], v222 offset:54272
	ds_read_b128 v[210:213], v222 offset:55296
	ds_read_b128 v[214:217], v222 offset:56320
	global_load_lds_dwordx4 v[218:219], off
	s_add_i32 m0, s6, 0x2000
	v_lshl_add_u64 v[218:219], s[46:47], 0, v[136:137]
	s_add_u32 s46, s48, 0x42000
	s_addc_u32 s47, s49, 0
	s_add_i32 s6, s7, s25
	global_load_lds_dwordx4 v[218:219], off
	v_lshl_add_u64 v[218:219], s[46:47], 0, v[138:139]
	s_mov_b32 m0, s6
	v_lshl_add_u64 v[198:199], v[198:199], 0, s[36:37]
	global_load_lds_dwordx4 v[218:219], off
	v_lshl_add_u64 v[218:219], s[46:47], 0, v[136:137]
	s_add_i32 m0, s6, 0x2000
	s_nop 0
	global_load_lds_dwordx4 v[218:219], off
	s_mov_b32 m0, s58
	s_nop 0
	global_load_lds_dwordx4 v[198:199], off
	v_lshl_add_u64 v[198:199], v[200:201], 0, s[36:37]
	s_mov_b32 m0, s59
	s_nop 0
	global_load_lds_dwordx4 v[198:199], off
	s_waitcnt vmcnt(9)
	s_waitcnt lgkmcnt(0)
	s_barrier
	s_setprio 1
	s_waitcnt lgkmcnt(0)
	v_mfma_f32_16x16x32_bf16 v[60:63], v[112:115], v[164:167], v[60:63]
	v_mfma_f32_16x16x32_bf16 v[56:59], v[128:131], v[164:167], v[56:59]
	v_mfma_f32_16x16x32_bf16 v[44:47], v[112:115], v[172:175], v[44:47]
	v_mfma_f32_16x16x32_bf16 v[40:43], v[128:131], v[172:175], v[40:43]
	v_mfma_f32_16x16x32_bf16 v[28:31], v[112:115], v[188:191], v[28:31]
	v_mfma_f32_16x16x32_bf16 v[24:27], v[128:131], v[188:191], v[24:27]
	v_mfma_f32_16x16x32_bf16 v[12:15], v[112:115], v[210:213], v[12:15]
	v_mfma_f32_16x16x32_bf16 v[8:11], v[128:131], v[210:213], v[8:11]
	v_mfma_f32_16x16x32_bf16 v[60:63], v[116:119], v[168:171], v[60:63]
	v_mfma_f32_16x16x32_bf16 v[56:59], v[132:135], v[168:171], v[56:59]
	v_mfma_f32_16x16x32_bf16 v[44:47], v[116:119], v[176:179], v[44:47]
	v_mfma_f32_16x16x32_bf16 v[40:43], v[132:135], v[176:179], v[40:43]
	v_mfma_f32_16x16x32_bf16 v[28:31], v[116:119], v[206:209], v[28:31]
	v_mfma_f32_16x16x32_bf16 v[24:27], v[132:135], v[206:209], v[24:27]
	v_mfma_f32_16x16x32_bf16 v[12:15], v[116:119], v[214:217], v[12:15]
	v_mfma_f32_16x16x32_bf16 v[8:11], v[132:135], v[214:217], v[8:11]
	v_mfma_f32_16x16x32_bf16 v[52:55], v[140:143], v[164:167], v[52:55]
	v_mfma_f32_16x16x32_bf16 v[48:51], v[156:159], v[164:167], v[48:51]
	v_mfma_f32_16x16x32_bf16 v[36:39], v[140:143], v[172:175], v[36:39]
	v_mfma_f32_16x16x32_bf16 v[32:35], v[156:159], v[172:175], v[32:35]
	v_mfma_f32_16x16x32_bf16 v[20:23], v[140:143], v[188:191], v[20:23]
	v_mfma_f32_16x16x32_bf16 v[16:19], v[156:159], v[188:191], v[16:19]
	v_mfma_f32_16x16x32_bf16 v[4:7], v[140:143], v[210:213], v[4:7]
	v_mfma_f32_16x16x32_bf16 v[0:3], v[156:159], v[210:213], v[0:3]
	v_mfma_f32_16x16x32_bf16 v[52:55], v[144:147], v[168:171], v[52:55]
	v_mfma_f32_16x16x32_bf16 v[48:51], v[160:163], v[168:171], v[48:51]
	v_mfma_f32_16x16x32_bf16 v[36:39], v[144:147], v[176:179], v[36:39]
	v_mfma_f32_16x16x32_bf16 v[32:35], v[160:163], v[176:179], v[32:35]
	v_mfma_f32_16x16x32_bf16 v[20:23], v[144:147], v[206:209], v[20:23]
	v_mfma_f32_16x16x32_bf16 v[16:19], v[160:163], v[206:209], v[16:19]
	v_mfma_f32_16x16x32_bf16 v[4:7], v[144:147], v[214:217], v[4:7]
	v_mfma_f32_16x16x32_bf16 v[0:3], v[160:163], v[214:217], v[0:3]
	s_setprio 0
	s_barrier
	s_add_i32 s77, s77, 2
	s_add_u32 s75, s75, 0x80000
	s_addc_u32 s76, s76, 0
	s_cmp_gt_u32 s77, 29
	s_mov_b64 s[46:47], s[42:43]
	s_cbranch_scc0 .LBB0_727
;     __device__ __forceinline__ void operator()(const f32x4 (&acc)[2][2][4][2], const Unit& u, int wr, int wc, int fr, int fq, const LAS float*) const {
;         const int row0 = u.pm * BM + wr * 64 + fr, col0 = u.pn * BM + wc * 32 + 8 * fq;
;         f32x4 bv[2][2], sv[2][2];
; #pragma unroll
;         for (int bj = 0; bj < 2; ++bj)
; #pragma unroll
;             for (int n = 0; n < 2; ++n) { bv[bj][n] = HB ? *(const f32x4*)(bias + col0 + bj * HALF + 4 * n) : (f32x4){0.f, 0.f, 0.f, 0.f};
;                                            sv[bj][n] = HB ? *(const f32x4*)(scale + col0 + bj * HALF + 4 * n) : (f32x4){1.f, 1.f, 1.f, 1.f}; }
;         constexpr int NB = HB ? 4 : 2, MB = 4 / (NB / 2);
; #pragma unroll
;         for (int am = 0; am < NB; ++am) { const int ai = am / (NB / 2), m0 = (am % (NB / 2)) * MB;
;             f32x4 xo[4][2][2];
; #pragma unroll
;             for (int m = m0; m < m0 + MB; ++m) { const float* xr = Xs + (size_t)(row0 + ai * HALF + m * 16) * DM + col0;
; #pragma unroll
;                 for (int bj = 0; bj < 2; ++bj) { xo[m][bj][0] = *(const f32x4*)(xr + bj * HALF); xo[m][bj][1] = *(const f32x4*)(xr + bj * HALF + 4); } }
; #pragma unroll
;             for (int m = m0; m < m0 + MB; ++m) { const int row = row0 + ai * HALF + m * 16; float ss = 0.f;
;                 float* xr = X + (size_t)row * DM + col0; bf16_t* xb = XB + (size_t)row * ALD + col0;
; #pragma unroll
;                 for (int bj = 0; bj < 2; ++bj) { f32x4 x0 = xo[m][bj][0], x1 = xo[m][bj][1];
;                     if (HB) { x0 += (acc[ai][bj][m][0] + bv[bj][0]) * sv[bj][0]; x1 += (acc[ai][bj][m][1] + bv[bj][1]) * sv[bj][1]; } else { x0 += acc[ai][bj][m][0]; x1 += acc[ai][bj][m][1]; }
;                     *(f32x4*)(xr + bj * HALF) = x0; *(f32x4*)(xr + bj * HALF + 4) = x1;
;                     ss += (x0[0] * x0[0] + x0[1] * x0[1]) + (x0[2] * x0[2] + x0[3] * x0[3]) + (x1[0] * x1[0] + x1[1] * x1[1]) + (x1[2] * x1[2] + x1[3] * x1[3]);
;                     u32x4 w; w.x = cvt_pk_bf16(x0[0], x0[1]); w.y = cvt_pk_bf16(x0[2], x0[3]); w.z = cvt_pk_bf16(x1[0], x1[1]); w.w = cvt_pk_bf16(x1[2], x1[3]);
;                     if (feeds) *(u32x4*)(xb + bj * HALF) = w; }
;                 ss += __shfl_xor(ss, 16); ss += __shfl_xor(ss, 32);
;                 if (fq == 0 && feeds) part[(size_t)row * NPART + u.pn * 4 + wc] = ss; }
	v_lshl_or_b32 v188, s12, 8, v221
	v_lshl_add_u32 v190, s13, 8, v197
	v_ashrrev_i32_e32 v189, 31, v188
	v_lshlrev_b64 v[198:199], 2, v[188:189]
	v_ashrrev_i32_e32 v191, 31, v190
	v_lshl_add_u64 v[206:207], s[22:23], 0, v[198:199]
	v_lshlrev_b64 v[200:201], 13, v[190:191]
	v_lshl_add_u64 v[112:113], v[206:207], 0, v[200:201]
	global_load_dwordx4 v[224:227], v[112:113], off offset:16
	global_load_dwordx4 v[228:231], v[112:113], off
	global_load_dwordx4 v[232:235], v[112:113], off offset:528
	global_load_dwordx4 v[244:247], v[112:113], off offset:512
	v_or_b32_e32 v214, 16, v190
	v_ashrrev_i32_e32 v215, 31, v214
	v_or_b32_e32 v210, 32, v190
	v_or_b32_e32 v208, 48, v190
	v_lshlrev_b64 v[218:219], 13, v[214:215]
	v_ashrrev_i32_e32 v211, 31, v210
	v_ashrrev_i32_e32 v209, 31, v208
	v_lshl_add_u64 v[112:113], v[206:207], 0, v[218:219]
	v_lshlrev_b64 v[216:217], 13, v[210:211]
	v_lshlrev_b64 v[212:213], 13, v[208:209]
	global_load_dwordx4 v[172:175], v[112:113], off offset:16
	global_load_dwordx4 v[176:179], v[112:113], off
	global_load_dwordx4 v[164:167], v[112:113], off offset:528
	global_load_dwordx4 v[168:171], v[112:113], off offset:512
	v_lshl_add_u64 v[112:113], v[206:207], 0, v[216:217]
	v_lshl_add_u64 v[116:117], v[206:207], 0, v[212:213]
	global_load_dwordx4 v[156:159], v[112:113], off offset:16
	global_load_dwordx4 v[160:163], v[112:113], off
	global_load_dwordx4 v[128:131], v[112:113], off offset:528
	global_load_dwordx4 v[144:147], v[112:113], off offset:512
	global_load_dwordx4 v[132:135], v[116:117], off offset:16
	global_load_dwordx4 v[140:143], v[116:117], off
	s_nop 0
	global_load_dwordx4 v[112:115], v[116:117], off offset:528
	s_nop 0
	global_load_dwordx4 v[116:119], v[116:117], off offset:512
	v_lshl_add_u64 v[200:201], s[82:83], 0, v[200:201]
	v_lshl_add_u64 v[198:199], v[200:201], 0, v[198:199]
	v_mov_b64_e32 v[200:201], s[4:5]
	s_lshl_b32 s42, s12, 2
	v_mad_i64_i32 v[200:201], s[12:13], v190, s66, v[200:201]
	v_lshl_add_u64 v[200:201], v[188:189], 1, v[200:201]
	s_ashr_i32 s43, s42, 31
	s_waitcnt vmcnt(12)
	v_pk_add_f32 v[148:149], v[148:149], v[224:225]
	v_pk_add_f32 v[154:155], v[154:155], v[230:231]
	v_pk_add_f32 v[152:153], v[152:153], v[228:229]
	v_mul_f32_e32 v224, v155, v155
	v_mul_f32_e32 v223, v153, v153
	v_fmac_f32_e32 v223, v152, v152
	v_fmac_f32_e32 v224, v154, v154
	v_add_f32_e32 v223, v223, v224
	v_mul_f32_e32 v224, v149, v149
	v_pk_add_f32 v[126:127], v[126:127], v[246:247]
	v_pk_add_f32 v[124:125], v[124:125], v[244:245]
	v_pk_add_f32 v[150:151], v[150:151], v[226:227]
	global_store_dwordx4 v[198:199], v[152:155], off
	global_store_dwordx4 v[198:199], v[148:151], off offset:16
	v_fmac_f32_e32 v224, v148, v148
	v_cvt_pk_bf16_f32 v152, v152, v153
	v_cvt_pk_bf16_f32 v153, v154, v155
	v_cvt_pk_bf16_f32 v154, v148, v149
	v_pk_add_f32 v[120:121], v[120:121], v[232:233]
	v_mul_f32_e32 v148, v125, v125
	v_mul_f32_e32 v149, v127, v127
	v_fmac_f32_e32 v148, v124, v124
	v_fmac_f32_e32 v149, v126, v126
	v_add_f32_e32 v148, v148, v149
	v_mul_f32_e32 v149, v121, v121
	v_cvt_pk_bf16_f32 v155, v150, v151
	global_store_dwordx4 v[200:201], v[152:155], off
	v_pk_add_f32 v[122:123], v[122:123], v[234:235]
	global_store_dwordx4 v[198:199], v[124:127], off offset:512
	global_store_dwordx4 v[198:199], v[120:123], off offset:528
	v_fmac_f32_e32 v149, v120, v120
	v_cvt_pk_bf16_f32 v124, v124, v125
	v_cvt_pk_bf16_f32 v125, v126, v127
	v_cvt_pk_bf16_f32 v126, v120, v121
	v_add_f32_e32 v223, v223, v224
	v_and_b32_e32 v121, 64, v239
	v_mul_f32_e32 v224, v151, v151
	v_add_f32_e32 v148, v148, v149
	v_mul_f32_e32 v149, v123, v123
	v_xor_b32_e32 v120, 16, v239
	v_add_u32_e32 v121, 64, v121
	v_fmac_f32_e32 v224, v150, v150
	v_fmac_f32_e32 v149, v122, v122
	v_cmp_lt_i32_e32 vcc, v120, v121
	v_add_f32_e32 v223, v224, v223
	v_add_f32_e32 v148, v149, v148
	v_cndmask_b32_e32 v120, v239, v120, vcc
	v_add_f32_e32 v148, v223, v148
	v_cvt_pk_bf16_f32 v127, v122, v123
	global_store_dwordx4 v[200:201], v[124:127], off offset:256
	v_xor_b32_e32 v122, 32, v239
	v_cmp_lt_i32_e32 vcc, v122, v121
	v_lshlrev_b32_e32 v126, 2, v120
	ds_bpermute_b32 v120, v126, v148
	v_cndmask_b32_e32 v121, v239, v122, vcc
	v_lshlrev_b32_e32 v127, 2, v121
	s_waitcnt lgkmcnt(0)
	v_add_f32_e32 v120, v148, v120
	ds_bpermute_b32 v121, v127, v120
	s_and_saveexec_b64 s[46:47], s[38:39]
	s_cbranch_execz .LBB0_730
	v_lshlrev_b64 v[122:123], 7, v[190:191]
	v_lshl_add_u64 v[122:123], s[94:95], 0, v[122:123]
	v_lshl_add_u64 v[122:123], s[42:43], 2, v[122:123]
	s_lshl_b32 s30, s57, 2
	v_lshl_add_u64 v[122:123], v[122:123], 0, s[30:31]
	s_waitcnt lgkmcnt(0)
	v_add_f32_e32 v120, v120, v121
	global_store_dword v[122:123], v120, off

; #define PG8_STAGE(bufoff, gbase, voff) do { _Pragma("unroll") for (int _i = 0; _i < 2; ++_i) \
;         __builtin_amdgcn_global_load_lds((const unsigned*)((const char*)(gbase) + (voff)[_i]), (LAS unsigned*)(lds + (bufoff) + ldsw + _i * 8192), 16, 0, 0); } while (0)
; #define PG8_LDA(dst, b, h) do { _Pragma("unroll") for (int m = 0; m < 4; ++m) _Pragma("unroll") for (int k = 0; k < 2; ++k) dst[m][k] = *(const LAS bf16x8*)(lds + PG8_SA(b, h) + aoff + m * 2048 + k * 1024); } while (0)
; #define PG8_LDB(dst, b, h) do { _Pragma("unroll") for (int n = 0; n < 2; ++n) _Pragma("unroll") for (int k = 0; k < 2; ++k) dst[n][k] = *(const LAS bf16x8*)(lds + PG8_SB(b, h) + boff + n * 2048 + k * 1024); } while (0)
; #define PG8_MMA(ai, bj, At, Bt) do { __builtin_amdgcn_s_setprio(1); _Pragma("unroll") for (int m = 0; m < 4; ++m) _Pragma("unroll") for (int n = 0; n < 2; ++n) _Pragma("unroll") for (int k = 0; k < 2; ++k) \
;         acc[ai][bj][m][n] = __builtin_amdgcn_mfma_f32_16x16x32_bf16(Bt[n][k], At[m][k], acc[ai][bj][m][n], 0, 0, 0); __builtin_amdgcn_s_setprio(0); } while (0)
; #define PG8_WAIT_V(n) asm volatile("s_waitcnt vmcnt(" #n ")" ::: "memory")
; #define PG8_WAIT_L(n) asm volatile("s_waitcnt lgkmcnt(" #n ")" ::: "memory")
; #define PG8_BAR __builtin_amdgcn_s_barrier()
; #define PG8_SCHED __builtin_amdgcn_sched_barrier(0)
; template <class Epi, bool ALIGN_EPI>
; __device__ __forceinline__ void gemm_phase(LAS unsigned char* lds, const Gemm g, int G, int cid, const Epi& E) {
;     ...
;         for (int t = 0; t < nt; t += 2) {
;             const bool last = (t == nt - 2);
;             const char* a1 = cA + (size_t)(t + 1) * kA;
;             const char* a2 = last ? nA : cA + (size_t)(t + 2) * kA; const char* b2 = last ? nB : cB + (size_t)(t + 2) * kB;
;             const char* a3 = a2 + kA; const char* b3 = b2 + kB;
;             PG8_LDB(B0, 0, 0); PG8_LDB(B1, 0, 1); PG8_SCHED; PG8_LDA(At, 0, 0); PG8_STAGE(PG8_SA(1, 1), a1 + hA, voffA);
;             PG8_WAIT_V(8); PG8_WAIT_L(0); PG8_BAR; PG8_MMA(0, 0, At, B0); PG8_MMA(0, 1, At, B1); PG8_BAR; PG8_SCHED;
;             PG8_LDA(At, 0, 1); PG8_STAGE(PG8_SB(0, 0), b2, voffB); PG8_STAGE(PG8_SB(0, 1), b2 + hB, voffB); PG8_STAGE(PG8_SA(0, 0), a2, voffA);
;             PG8_WAIT_V(8); PG8_WAIT_L(0); PG8_BAR; PG8_MMA(1, 0, At, B0); PG8_MMA(1, 1, At, B1); PG8_BAR; PG8_SCHED;
.LBB0_813:
	s_add_u32 s54, s52, 0x100
	s_addc_u32 s55, s53, 0
	s_and_b64 s[6:7], exec, s[58:59]
	s_cselect_b32 s59, s45, s55
	s_cselect_b32 s58, s44, s54
	s_add_i32 s6, 0, 0x10000
	s_add_i32 s92, 0, 0x14000
	v_add_u32_e32 v144, s6, v176
	v_add_u32_e32 v160, s92, v176
	ds_read_b128 v[128:131], v144
	ds_read_b128 v[132:135], v144 offset:1024
	ds_read_b128 v[140:143], v144 offset:2048
	ds_read_b128 v[144:147], v144 offset:3072
	ds_read_b128 v[148:151], v160
	ds_read_b128 v[152:155], v160 offset:1024
	ds_read_b128 v[156:159], v160 offset:2048
	ds_read_b128 v[160:163], v160 offset:3072
	v_lshl_add_u64 v[198:199], s[52:53], 0, v[170:171]
	s_add_i32 m0, s13, 0xc000
	ds_read_b128 v[180:183], v179
	ds_read_b128 v[184:187], v179 offset:1024
	ds_read_b128 v[188:191], v179 offset:2048
	ds_read_b128 v[206:209], v179 offset:3072
	ds_read_b128 v[210:213], v179 offset:4096
	ds_read_b128 v[214:217], v179 offset:5120
	ds_read_b128 v[218:221], v179 offset:6144
	ds_read_b128 v[222:225], v179 offset:7168
	global_load_lds_dwordx4 v[198:199], off
	v_lshl_add_u64 v[198:199], s[52:53], 0, v[172:173]
	s_add_i32 m0, s13, 0xe000
	s_nop 0
	global_load_lds_dwordx4 v[198:199], off
	s_waitcnt vmcnt(8)
	s_waitcnt lgkmcnt(0)
	s_barrier
	s_setprio 1
	s_waitcnt lgkmcnt(0)
	v_mfma_f32_16x16x32_bf16 v[124:127], v[128:131], v[180:183], v[124:127]
	v_mfma_f32_16x16x32_bf16 v[120:123], v[140:143], v[180:183], v[120:123]
	v_mfma_f32_16x16x32_bf16 v[108:111], v[128:131], v[188:191], v[108:111]
	v_mfma_f32_16x16x32_bf16 v[104:107], v[140:143], v[188:191], v[104:107]
	v_mfma_f32_16x16x32_bf16 v[92:95], v[128:131], v[210:213], v[92:95]
	v_mfma_f32_16x16x32_bf16 v[88:91], v[140:143], v[210:213], v[88:91]
	v_mfma_f32_16x16x32_bf16 v[76:79], v[128:131], v[218:221], v[76:79]
	v_mfma_f32_16x16x32_bf16 v[72:75], v[140:143], v[218:221], v[72:75]
	v_mfma_f32_16x16x32_bf16 v[124:127], v[132:135], v[184:187], v[124:127]
	v_mfma_f32_16x16x32_bf16 v[120:123], v[144:147], v[184:187], v[120:123]
	v_mfma_f32_16x16x32_bf16 v[108:111], v[132:135], v[206:209], v[108:111]
	v_mfma_f32_16x16x32_bf16 v[104:107], v[144:147], v[206:209], v[104:107]
	v_mfma_f32_16x16x32_bf16 v[92:95], v[132:135], v[214:217], v[92:95]
	v_mfma_f32_16x16x32_bf16 v[88:91], v[144:147], v[214:217], v[88:91]
	v_mfma_f32_16x16x32_bf16 v[76:79], v[132:135], v[222:225], v[76:79]
	v_mfma_f32_16x16x32_bf16 v[72:75], v[144:147], v[222:225], v[72:75]
	v_mfma_f32_16x16x32_bf16 v[116:119], v[148:151], v[180:183], v[116:119]
	v_mfma_f32_16x16x32_bf16 v[112:115], v[156:159], v[180:183], v[112:115]
	v_mfma_f32_16x16x32_bf16 v[100:103], v[148:151], v[188:191], v[100:103]
	v_mfma_f32_16x16x32_bf16 v[96:99], v[156:159], v[188:191], v[96:99]
	v_mfma_f32_16x16x32_bf16 v[84:87], v[148:151], v[210:213], v[84:87]
	v_mfma_f32_16x16x32_bf16 v[80:83], v[156:159], v[210:213], v[80:83]
	v_mfma_f32_16x16x32_bf16 v[68:71], v[148:151], v[218:221], v[68:71]
	v_mfma_f32_16x16x32_bf16 v[64:67], v[156:159], v[218:221], v[64:67]
	v_mfma_f32_16x16x32_bf16 v[116:119], v[152:155], v[184:187], v[116:119]
	v_mfma_f32_16x16x32_bf16 v[112:115], v[160:163], v[184:187], v[112:115]
	v_mfma_f32_16x16x32_bf16 v[100:103], v[152:155], v[206:209], v[100:103]
	v_mfma_f32_16x16x32_bf16 v[96:99], v[160:163], v[206:209], v[96:99]
	v_mfma_f32_16x16x32_bf16 v[84:87], v[152:155], v[214:217], v[84:87]
	v_mfma_f32_16x16x32_bf16 v[80:83], v[160:163], v[214:217], v[80:83]
	v_mfma_f32_16x16x32_bf16 v[68:71], v[152:155], v[222:225], v[68:71]
	v_mfma_f32_16x16x32_bf16 v[64:67], v[160:163], v[222:225], v[64:67]
	s_setprio 0
	s_barrier
	s_add_i32 s6, s6, s12
	v_lshl_add_u64 v[198:199], s[56:57], 0, v[164:165]
	s_mov_b32 m0, s6
	ds_read_b128 v[180:183], v179 offset:16384
	ds_read_b128 v[184:187], v179 offset:17408
	ds_read_b128 v[188:191], v179 offset:18432
	ds_read_b128 v[206:209], v179 offset:19456
	ds_read_b128 v[210:213], v179 offset:20480
	ds_read_b128 v[214:217], v179 offset:21504
	ds_read_b128 v[218:221], v179 offset:22528
	ds_read_b128 v[222:225], v179 offset:23552
	global_load_lds_dwordx4 v[198:199], off
	s_add_i32 m0, s6, 0x2000
	s_add_u32 s6, s56, 0x2000
	v_lshl_add_u64 v[198:199], s[56:57], 0, v[168:169]
	s_addc_u32 s7, s57, 0
	s_add_i32 s52, s92, s12
	global_load_lds_dwordx4 v[198:199], off
	v_lshl_add_u64 v[198:199], s[6:7], 0, v[164:165]
	s_mov_b32 m0, s52
	v_lshl_add_u64 v[200:201], s[58:59], 0, v[166:167]
	global_load_lds_dwordx4 v[198:199], off
	v_lshl_add_u64 v[198:199], s[6:7], 0, v[168:169]
	s_add_i32 m0, s52, 0x2000
	s_nop 0
	global_load_lds_dwordx4 v[198:199], off
	v_lshl_add_u64 v[198:199], s[58:59], 0, v[136:137]
	s_mov_b32 m0, s13
	s_nop 0
	global_load_lds_dwordx4 v[198:199], off
	s_mov_b32 m0, s24
	s_nop 0
	global_load_lds_dwordx4 v[200:201], off
	s_waitcnt vmcnt(8)
	s_waitcnt lgkmcnt(0)
	s_barrier
; #define PG8_STAGE(bufoff, gbase, voff) do { _Pragma("unroll") for (int _i = 0; _i < 2; ++_i) \
;         __builtin_amdgcn_global_load_lds((const unsigned*)((const char*)(gbase) + (voff)[_i]), (LAS unsigned*)(lds + (bufoff) + ldsw + _i * 8192), 16, 0, 0); } while (0)
; #define PG8_LDA(dst, b, h) do { _Pragma("unroll") for (int m = 0; m < 4; ++m) _Pragma("unroll") for (int k = 0; k < 2; ++k) dst[m][k] = *(const LAS bf16x8*)(lds + PG8_SA(b, h) + aoff + m * 2048 + k * 1024); } while (0)
; #define PG8_LDB(dst, b, h) do { _Pragma("unroll") for (int n = 0; n < 2; ++n) _Pragma("unroll") for (int k = 0; k < 2; ++k) dst[n][k] = *(const LAS bf16x8*)(lds + PG8_SB(b, h) + boff + n * 2048 + k * 1024); } while (0)
; #define PG8_MMA(ai, bj, At, Bt) do { __builtin_amdgcn_s_setprio(1); _Pragma("unroll") for (int m = 0; m < 4; ++m) _Pragma("unroll") for (int n = 0; n < 2; ++n) _Pragma("unroll") for (int k = 0; k < 2; ++k) \
;         acc[ai][bj][m][n] = __builtin_amdgcn_mfma_f32_16x16x32_bf16(Bt[n][k], At[m][k], acc[ai][bj][m][n], 0, 0, 0); __builtin_amdgcn_s_setprio(0); } while (0)
; #define PG8_WAIT_V(n) asm volatile("s_waitcnt vmcnt(" #n ")" ::: "memory")
; #define PG8_WAIT_L(n) asm volatile("s_waitcnt lgkmcnt(" #n ")" ::: "memory")
; #define PG8_BAR __builtin_amdgcn_s_barrier()
; #define PG8_SCHED __builtin_amdgcn_sched_barrier(0)
; template <class Epi, bool ALIGN_EPI>
; __device__ __forceinline__ void gemm_phase(LAS unsigned char* lds, const Gemm g, int G, int cid, const Epi& E) {
;     ...
;             PG8_WAIT_V(8); PG8_WAIT_L(0); PG8_BAR; PG8_MMA(1, 0, At, B0); PG8_MMA(1, 1, At, B1); PG8_BAR; PG8_SCHED;
;             PG8_LDB(B0, 1, 0); PG8_LDB(B1, 1, 1); PG8_SCHED; PG8_LDA(At, 1, 0); PG8_STAGE(PG8_SA(0, 1), a2 + hA, voffA);
;             PG8_WAIT_V(8); PG8_WAIT_L(0); PG8_BAR; PG8_MMA(0, 0, At, B0); PG8_MMA(0, 1, At, B1); PG8_BAR; PG8_SCHED;
	s_setprio 1
	s_waitcnt lgkmcnt(0)
	v_mfma_f32_16x16x32_bf16 v[60:63], v[128:131], v[180:183], v[60:63]
	v_mfma_f32_16x16x32_bf16 v[56:59], v[140:143], v[180:183], v[56:59]
	v_mfma_f32_16x16x32_bf16 v[44:47], v[128:131], v[188:191], v[44:47]
	v_mfma_f32_16x16x32_bf16 v[40:43], v[140:143], v[188:191], v[40:43]
	v_mfma_f32_16x16x32_bf16 v[28:31], v[128:131], v[210:213], v[28:31]
	v_mfma_f32_16x16x32_bf16 v[24:27], v[140:143], v[210:213], v[24:27]
	v_mfma_f32_16x16x32_bf16 v[12:15], v[128:131], v[218:221], v[12:15]
	v_mfma_f32_16x16x32_bf16 v[8:11], v[140:143], v[218:221], v[8:11]
	v_mfma_f32_16x16x32_bf16 v[60:63], v[132:135], v[184:187], v[60:63]
	v_mfma_f32_16x16x32_bf16 v[56:59], v[144:147], v[184:187], v[56:59]
	v_mfma_f32_16x16x32_bf16 v[44:47], v[132:135], v[206:209], v[44:47]
	v_mfma_f32_16x16x32_bf16 v[40:43], v[144:147], v[206:209], v[40:43]
	v_mfma_f32_16x16x32_bf16 v[28:31], v[132:135], v[214:217], v[28:31]
	v_mfma_f32_16x16x32_bf16 v[24:27], v[144:147], v[214:217], v[24:27]
	v_mfma_f32_16x16x32_bf16 v[12:15], v[132:135], v[222:225], v[12:15]
	v_mfma_f32_16x16x32_bf16 v[8:11], v[144:147], v[222:225], v[8:11]
	v_mfma_f32_16x16x32_bf16 v[52:55], v[148:151], v[180:183], v[52:55]
	v_mfma_f32_16x16x32_bf16 v[48:51], v[156:159], v[180:183], v[48:51]
	v_mfma_f32_16x16x32_bf16 v[36:39], v[148:151], v[188:191], v[36:39]
	v_mfma_f32_16x16x32_bf16 v[32:35], v[156:159], v[188:191], v[32:35]
	v_mfma_f32_16x16x32_bf16 v[20:23], v[148:151], v[210:213], v[20:23]
	v_mfma_f32_16x16x32_bf16 v[16:19], v[156:159], v[210:213], v[16:19]
	v_mfma_f32_16x16x32_bf16 v[4:7], v[148:151], v[218:221], v[4:7]
	v_mfma_f32_16x16x32_bf16 v[0:3], v[156:159], v[218:221], v[0:3]
	v_mfma_f32_16x16x32_bf16 v[52:55], v[152:155], v[184:187], v[52:55]
	v_mfma_f32_16x16x32_bf16 v[48:51], v[160:163], v[184:187], v[48:51]
	v_mfma_f32_16x16x32_bf16 v[36:39], v[152:155], v[206:209], v[36:39]
	v_mfma_f32_16x16x32_bf16 v[32:35], v[160:163], v[206:209], v[32:35]
	v_mfma_f32_16x16x32_bf16 v[20:23], v[152:155], v[214:217], v[20:23]
	v_mfma_f32_16x16x32_bf16 v[16:19], v[160:163], v[214:217], v[16:19]
	v_mfma_f32_16x16x32_bf16 v[4:7], v[152:155], v[222:225], v[4:7]
	v_mfma_f32_16x16x32_bf16 v[0:3], v[160:163], v[222:225], v[0:3]
	s_setprio 0
	s_barrier
	s_add_i32 s52, 0, 0x18000
	s_add_i32 s53, 0, 0x1c000
	v_add_u32_e32 v144, s52, v176
	v_add_u32_e32 v160, s53, v176
	ds_read_b128 v[128:131], v144
	ds_read_b128 v[132:135], v144 offset:1024
	ds_read_b128 v[140:143], v144 offset:2048
	ds_read_b128 v[144:147], v144 offset:3072
	ds_read_b128 v[148:151], v160
	ds_read_b128 v[152:155], v160 offset:1024
	ds_read_b128 v[156:159], v160 offset:2048
	ds_read_b128 v[160:163], v160 offset:3072
	s_add_u32 s6, s58, 0x84000
	s_addc_u32 s7, s59, 0
	s_mov_b32 m0, s25
	v_lshl_add_u64 v[226:227], s[6:7], 0, v[136:137]
	ds_read_b128 v[180:183], v179 offset:32768
	ds_read_b128 v[184:187], v179 offset:33792
	ds_read_b128 v[188:191], v179 offset:34816
	ds_read_b128 v[206:209], v179 offset:35840
	ds_read_b128 v[210:213], v179 offset:36864
	ds_read_b128 v[214:217], v179 offset:37888
	ds_read_b128 v[218:221], v179 offset:38912
	ds_read_b128 v[222:225], v179 offset:39936
	global_load_lds_dwordx4 v[226:227], off
	v_lshl_add_u64 v[226:227], s[6:7], 0, v[166:167]
	s_mov_b32 m0, s74
	s_nop 0
	global_load_lds_dwordx4 v[226:227], off
	s_waitcnt vmcnt(8)
	s_waitcnt lgkmcnt(0)
	s_barrier
	s_setprio 1
	s_waitcnt lgkmcnt(0)
	v_mfma_f32_16x16x32_bf16 v[124:127], v[128:131], v[180:183], v[124:127]
	v_mfma_f32_16x16x32_bf16 v[120:123], v[140:143], v[180:183], v[120:123]
	v_mfma_f32_16x16x32_bf16 v[108:111], v[128:131], v[188:191], v[108:111]
	v_mfma_f32_16x16x32_bf16 v[104:107], v[140:143], v[188:191], v[104:107]
	v_mfma_f32_16x16x32_bf16 v[92:95], v[128:131], v[210:213], v[92:95]
	v_mfma_f32_16x16x32_bf16 v[88:91], v[140:143], v[210:213], v[88:91]
	v_mfma_f32_16x16x32_bf16 v[76:79], v[128:131], v[218:221], v[76:79]
	v_mfma_f32_16x16x32_bf16 v[72:75], v[140:143], v[218:221], v[72:75]
	v_mfma_f32_16x16x32_bf16 v[124:127], v[132:135], v[184:187], v[124:127]
	v_mfma_f32_16x16x32_bf16 v[120:123], v[144:147], v[184:187], v[120:123]
	v_mfma_f32_16x16x32_bf16 v[108:111], v[132:135], v[206:209], v[108:111]
	v_mfma_f32_16x16x32_bf16 v[104:107], v[144:147], v[206:209], v[104:107]
	v_mfma_f32_16x16x32_bf16 v[92:95], v[132:135], v[214:217], v[92:95]
	v_mfma_f32_16x16x32_bf16 v[88:91], v[144:147], v[214:217], v[88:91]
	v_mfma_f32_16x16x32_bf16 v[76:79], v[132:135], v[222:225], v[76:79]
	v_mfma_f32_16x16x32_bf16 v[72:75], v[144:147], v[222:225], v[72:75]
	v_mfma_f32_16x16x32_bf16 v[116:119], v[148:151], v[180:183], v[116:119]
	v_mfma_f32_16x16x32_bf16 v[112:115], v[156:159], v[180:183], v[112:115]
	v_mfma_f32_16x16x32_bf16 v[100:103], v[148:151], v[188:191], v[100:103]
	v_mfma_f32_16x16x32_bf16 v[96:99], v[156:159], v[188:191], v[96:99]
	v_mfma_f32_16x16x32_bf16 v[84:87], v[148:151], v[210:213], v[84:87]
	v_mfma_f32_16x16x32_bf16 v[80:83], v[156:159], v[210:213], v[80:83]
	v_mfma_f32_16x16x32_bf16 v[68:71], v[148:151], v[218:221], v[68:71]
	v_mfma_f32_16x16x32_bf16 v[64:67], v[156:159], v[218:221], v[64:67]
	v_mfma_f32_16x16x32_bf16 v[116:119], v[152:155], v[184:187], v[116:119]
	v_mfma_f32_16x16x32_bf16 v[112:115], v[160:163], v[184:187], v[112:115]
	v_mfma_f32_16x16x32_bf16 v[100:103], v[152:155], v[206:209], v[100:103]
	v_mfma_f32_16x16x32_bf16 v[96:99], v[160:163], v[206:209], v[96:99]
	v_mfma_f32_16x16x32_bf16 v[84:87], v[152:155], v[214:217], v[84:87]
	v_mfma_f32_16x16x32_bf16 v[80:83], v[160:163], v[214:217], v[80:83]
	v_mfma_f32_16x16x32_bf16 v[68:71], v[152:155], v[222:225], v[68:71]
	v_mfma_f32_16x16x32_bf16 v[64:67], v[160:163], v[222:225], v[64:67]
	s_setprio 0
	s_barrier
; #define PG8_STAGE(bufoff, gbase, voff) do { _Pragma("unroll") for (int _i = 0; _i < 2; ++_i) \
;         __builtin_amdgcn_global_load_lds((const unsigned*)((const char*)(gbase) + (voff)[_i]), (LAS unsigned*)(lds + (bufoff) + ldsw + _i * 8192), 16, 0, 0); } while (0)
; #define PG8_LDA(dst, b, h) do { _Pragma("unroll") for (int m = 0; m < 4; ++m) _Pragma("unroll") for (int k = 0; k < 2; ++k) dst[m][k] = *(const LAS bf16x8*)(lds + PG8_SA(b, h) + aoff + m * 2048 + k * 1024); } while (0)
; #define PG8_MMA(ai, bj, At, Bt) do { __builtin_amdgcn_s_setprio(1); _Pragma("unroll") for (int m = 0; m < 4; ++m) _Pragma("unroll") for (int n = 0; n < 2; ++n) _Pragma("unroll") for (int k = 0; k < 2; ++k) \
;         acc[ai][bj][m][n] = __builtin_amdgcn_mfma_f32_16x16x32_bf16(Bt[n][k], At[m][k], acc[ai][bj][m][n], 0, 0, 0); __builtin_amdgcn_s_setprio(0); } while (0)
; #define PG8_WAIT_V(n) asm volatile("s_waitcnt vmcnt(" #n ")" ::: "memory")
; #define PG8_WAIT_L(n) asm volatile("s_waitcnt lgkmcnt(" #n ")" ::: "memory")
; #define PG8_BAR __builtin_amdgcn_s_barrier()
; #define PG8_SCHED __builtin_amdgcn_sched_barrier(0)
; template <class Epi, bool ALIGN_EPI>
; __device__ __forceinline__ void gemm_phase(LAS unsigned char* lds, const Gemm g, int G, int cid, const Epi& E) {
;     ...
;             PG8_WAIT_V(8); PG8_WAIT_L(0); PG8_BAR; PG8_MMA(0, 0, At, B0); PG8_MMA(0, 1, At, B1); PG8_BAR; PG8_SCHED;
;             PG8_LDA(At, 1, 1); PG8_STAGE(PG8_SB(1, 0), b3, voffB); PG8_STAGE(PG8_SB(1, 1), b3 + hB, voffB); PG8_STAGE(PG8_SA(1, 0), a3, voffA);
;             PG8_WAIT_V(8); PG8_WAIT_L(0); PG8_BAR; PG8_MMA(1, 0, At, B0); PG8_MMA(1, 1, At, B1); PG8_BAR; PG8_SCHED;
;         }
	s_add_u32 s6, s56, 0x160000
	s_addc_u32 s7, s57, 0
	s_add_i32 s52, s52, s12
	v_lshl_add_u64 v[226:227], s[6:7], 0, v[164:165]
	s_mov_b32 m0, s52
	ds_read_b128 v[180:183], v179 offset:49152
	ds_read_b128 v[184:187], v179 offset:50176
	ds_read_b128 v[188:191], v179 offset:51200
	ds_read_b128 v[206:209], v179 offset:52224
	ds_read_b128 v[210:213], v179 offset:53248
	ds_read_b128 v[214:217], v179 offset:54272
	ds_read_b128 v[218:221], v179 offset:55296
	ds_read_b128 v[222:225], v179 offset:56320
	global_load_lds_dwordx4 v[226:227], off
	s_add_i32 m0, s52, 0x2000
	v_lshl_add_u64 v[226:227], s[6:7], 0, v[168:169]
	s_add_u32 s6, s56, 0x162000
	s_addc_u32 s7, s57, 0
	s_add_i32 s52, s53, s12
	global_load_lds_dwordx4 v[226:227], off
	v_lshl_add_u64 v[226:227], s[6:7], 0, v[164:165]
	s_mov_b32 m0, s52
	v_lshl_add_u64 v[198:199], v[198:199], 0, s[36:37]
	global_load_lds_dwordx4 v[226:227], off
	v_lshl_add_u64 v[226:227], s[6:7], 0, v[168:169]
	s_add_i32 m0, s52, 0x2000
	s_nop 0
	global_load_lds_dwordx4 v[226:227], off
	s_mov_b32 m0, s75
	s_nop 0
	global_load_lds_dwordx4 v[198:199], off
	v_lshl_add_u64 v[198:199], v[200:201], 0, s[36:37]
	s_mov_b32 m0, s76
	s_nop 0
	global_load_lds_dwordx4 v[198:199], off
	s_waitcnt vmcnt(8)
	s_waitcnt lgkmcnt(0)
	s_barrier
	s_setprio 1
	s_waitcnt lgkmcnt(0)
	v_mfma_f32_16x16x32_bf16 v[60:63], v[128:131], v[180:183], v[60:63]
	v_mfma_f32_16x16x32_bf16 v[56:59], v[140:143], v[180:183], v[56:59]
	v_mfma_f32_16x16x32_bf16 v[44:47], v[128:131], v[188:191], v[44:47]
	v_mfma_f32_16x16x32_bf16 v[40:43], v[140:143], v[188:191], v[40:43]
	v_mfma_f32_16x16x32_bf16 v[28:31], v[128:131], v[210:213], v[28:31]
	v_mfma_f32_16x16x32_bf16 v[24:27], v[140:143], v[210:213], v[24:27]
	v_mfma_f32_16x16x32_bf16 v[12:15], v[128:131], v[218:221], v[12:15]
	v_mfma_f32_16x16x32_bf16 v[8:11], v[140:143], v[218:221], v[8:11]
	v_mfma_f32_16x16x32_bf16 v[60:63], v[132:135], v[184:187], v[60:63]
	v_mfma_f32_16x16x32_bf16 v[56:59], v[144:147], v[184:187], v[56:59]
	v_mfma_f32_16x16x32_bf16 v[44:47], v[132:135], v[206:209], v[44:47]
	v_mfma_f32_16x16x32_bf16 v[40:43], v[144:147], v[206:209], v[40:43]
	v_mfma_f32_16x16x32_bf16 v[28:31], v[132:135], v[214:217], v[28:31]
	v_mfma_f32_16x16x32_bf16 v[24:27], v[144:147], v[214:217], v[24:27]
	v_mfma_f32_16x16x32_bf16 v[12:15], v[132:135], v[222:225], v[12:15]
	v_mfma_f32_16x16x32_bf16 v[8:11], v[144:147], v[222:225], v[8:11]
	v_mfma_f32_16x16x32_bf16 v[52:55], v[148:151], v[180:183], v[52:55]
	v_mfma_f32_16x16x32_bf16 v[48:51], v[156:159], v[180:183], v[48:51]
	v_mfma_f32_16x16x32_bf16 v[36:39], v[148:151], v[188:191], v[36:39]
	v_mfma_f32_16x16x32_bf16 v[32:35], v[156:159], v[188:191], v[32:35]
	v_mfma_f32_16x16x32_bf16 v[20:23], v[148:151], v[210:213], v[20:23]
	v_mfma_f32_16x16x32_bf16 v[16:19], v[156:159], v[210:213], v[16:19]
	v_mfma_f32_16x16x32_bf16 v[4:7], v[148:151], v[218:221], v[4:7]
	v_mfma_f32_16x16x32_bf16 v[0:3], v[156:159], v[218:221], v[0:3]
	v_mfma_f32_16x16x32_bf16 v[52:55], v[152:155], v[184:187], v[52:55]
	v_mfma_f32_16x16x32_bf16 v[48:51], v[160:163], v[184:187], v[48:51]
	v_mfma_f32_16x16x32_bf16 v[36:39], v[152:155], v[206:209], v[36:39]
	v_mfma_f32_16x16x32_bf16 v[32:35], v[160:163], v[206:209], v[32:35]
	v_mfma_f32_16x16x32_bf16 v[20:23], v[152:155], v[214:217], v[20:23]
	v_mfma_f32_16x16x32_bf16 v[16:19], v[160:163], v[214:217], v[16:19]
	v_mfma_f32_16x16x32_bf16 v[4:7], v[152:155], v[222:225], v[4:7]
	v_mfma_f32_16x16x32_bf16 v[0:3], v[160:163], v[222:225], v[0:3]
	s_setprio 0
	s_barrier
	s_add_i32 s91, s91, 2
	s_add_u32 s50, s50, 0x2c0000
	s_addc_u32 s51, s51, 0
	s_cmp_gt_u32 s91, 29
	s_mov_b64 s[52:53], s[54:55]
	s_cbranch_scc1 .LBB0_816

; #define PG8_STAGE(bufoff, gbase, voff) do { _Pragma("unroll") for (int _i = 0; _i < 2; ++_i) \
;         __builtin_amdgcn_global_load_lds((const unsigned*)((const char*)(gbase) + (voff)[_i]), (LAS unsigned*)(lds + (bufoff) + ldsw + _i * 8192), 16, 0, 0); } while (0)
; #define PG8_LDA(dst, b, h) do { _Pragma("unroll") for (int m = 0; m < 4; ++m) _Pragma("unroll") for (int k = 0; k < 2; ++k) dst[m][k] = *(const LAS bf16x8*)(lds + PG8_SA(b, h) + aoff + m * 2048 + k * 1024); } while (0)
; #define PG8_LDB(dst, b, h) do { _Pragma("unroll") for (int n = 0; n < 2; ++n) _Pragma("unroll") for (int k = 0; k < 2; ++k) dst[n][k] = *(const LAS bf16x8*)(lds + PG8_SB(b, h) + boff + n * 2048 + k * 1024); } while (0)
; #define PG8_MMA(ai, bj, At, Bt) do { __builtin_amdgcn_s_setprio(1); _Pragma("unroll") for (int m = 0; m < 4; ++m) _Pragma("unroll") for (int n = 0; n < 2; ++n) _Pragma("unroll") for (int k = 0; k < 2; ++k) \
;         acc[ai][bj][m][n] = __builtin_amdgcn_mfma_f32_16x16x32_bf16(Bt[n][k], At[m][k], acc[ai][bj][m][n], 0, 0, 0); __builtin_amdgcn_s_setprio(0); } while (0)
; #define PG8_WAIT_V(n) asm volatile("s_waitcnt vmcnt(" #n ")" ::: "memory")
; #define PG8_WAIT_L(n) asm volatile("s_waitcnt lgkmcnt(" #n ")" ::: "memory")
; #define PG8_BAR __builtin_amdgcn_s_barrier()
; #define PG8_SCHED __builtin_amdgcn_sched_barrier(0)
; template <class Epi, bool ALIGN_EPI>
; __device__ __forceinline__ void gemm_phase(LAS unsigned char* lds, const Gemm g, int G, int cid, const Epi& E) {
;     ...
;         for (int t = 0; t < nt; t += 2) {
;             const bool last = (t == nt - 2);
;             const char* a1 = cA + (size_t)(t + 1) * kA;
;             const char* a2 = last ? nA : cA + (size_t)(t + 2) * kA; const char* b2 = last ? nB : cB + (size_t)(t + 2) * kB;
;             const char* a3 = a2 + kA; const char* b3 = b2 + kB;
;             PG8_LDB(B0, 0, 0); PG8_LDB(B1, 0, 1); PG8_SCHED; PG8_LDA(At, 0, 0); PG8_STAGE(PG8_SA(1, 1), a1 + hA, voffA);
;             PG8_WAIT_V(8); PG8_WAIT_L(0); PG8_BAR; PG8_MMA(0, 0, At, B0); PG8_MMA(0, 1, At, B1); PG8_BAR; PG8_SCHED;
;             PG8_LDA(At, 0, 1); PG8_STAGE(PG8_SB(0, 0), b2, voffB); PG8_STAGE(PG8_SB(0, 1), b2 + hB, voffB); PG8_STAGE(PG8_SA(0, 0), a2, voffA);
;             PG8_WAIT_V(8); PG8_WAIT_L(0); PG8_BAR; PG8_MMA(1, 0, At, B0); PG8_MMA(1, 1, At, B1); PG8_BAR; PG8_SCHED;
.LBB0_927:
	s_add_u32 s40, s48, 0x100
	s_addc_u32 s41, s49, 0
	s_add_i32 s6, 0, 0x10000
	s_cmpk_eq_i32 s79, 0x54
	s_cselect_b32 s53, s45, s41
	s_cselect_b32 s52, s44, s40
	s_cselect_b32 s51, s30, s78
	s_cselect_b32 s50, s76, s77
	s_add_i32 s86, 0, 0x14000
	v_add_u32_e32 v144, s6, v243
	v_add_u32_e32 v160, s86, v243
	ds_read_b128 v[128:131], v144
	ds_read_b128 v[132:135], v144 offset:1024
	ds_read_b128 v[140:143], v144 offset:2048
	ds_read_b128 v[144:147], v144 offset:3072
	ds_read_b128 v[148:151], v160
	ds_read_b128 v[152:155], v160 offset:1024
	ds_read_b128 v[156:159], v160 offset:2048
	ds_read_b128 v[160:163], v160 offset:3072
	v_lshl_add_u64 v[198:199], s[48:49], 0, v[210:211]
	s_add_i32 m0, s12, 0xc000
	ds_read_b128 v[164:167], v245
	ds_read_b128 v[168:171], v245 offset:1024
	ds_read_b128 v[172:175], v245 offset:2048
	ds_read_b128 v[176:179], v245 offset:3072
	ds_read_b128 v[180:183], v245 offset:4096
	ds_read_b128 v[184:187], v245 offset:5120
	ds_read_b128 v[188:191], v245 offset:6144
	ds_read_b128 v[214:217], v245 offset:7168
	global_load_lds_dwordx4 v[198:199], off
	v_lshl_add_u64 v[198:199], s[48:49], 0, v[212:213]
	s_add_i32 m0, s12, 0xe000
	s_nop 0
	global_load_lds_dwordx4 v[198:199], off
	s_add_i32 vcc_lo, s79, 2
	s_lshl_b32 vcc_lo, vcc_lo, 15
	s_and_b32 vcc_lo, vcc_lo, 0x1f0000
	s_lshl_b32 vcc_hi, s75, 21
	s_add_i32 vcc_lo, vcc_lo, vcc_hi
	s_lshl_b32 vcc_hi, s25, 3
	s_add_i32 vcc_lo, vcc_lo, vcc_hi
	s_lshl_b32 vcc_hi, s74, 10
	s_add_i32 vcc_lo, vcc_lo, vcc_hi
	s_add_u32 vcc_lo, s82, vcc_lo
	s_addc_u32 vcc_hi, s83, 0
	s_mov_b32 m0, 0x22c00
	s_nop 0
	global_load_lds_dwordx4 v226, vcc
	s_waitcnt vmcnt(9)
	s_waitcnt lgkmcnt(0)
	s_barrier
	s_setprio 1
	s_waitcnt lgkmcnt(0)
	v_mfma_f32_16x16x32_bf16 v[124:127], v[128:131], v[164:167], v[124:127]
	v_mfma_f32_16x16x32_bf16 v[120:123], v[140:143], v[164:167], v[120:123]
	v_mfma_f32_16x16x32_bf16 v[108:111], v[128:131], v[172:175], v[108:111]
	v_mfma_f32_16x16x32_bf16 v[104:107], v[140:143], v[172:175], v[104:107]
	v_mfma_f32_16x16x32_bf16 v[92:95], v[128:131], v[180:183], v[92:95]
	v_mfma_f32_16x16x32_bf16 v[88:91], v[140:143], v[180:183], v[88:91]
	v_mfma_f32_16x16x32_bf16 v[76:79], v[128:131], v[188:191], v[76:79]
	v_mfma_f32_16x16x32_bf16 v[72:75], v[140:143], v[188:191], v[72:75]
	v_mfma_f32_16x16x32_bf16 v[124:127], v[132:135], v[168:171], v[124:127]
	v_mfma_f32_16x16x32_bf16 v[120:123], v[144:147], v[168:171], v[120:123]
	v_mfma_f32_16x16x32_bf16 v[108:111], v[132:135], v[176:179], v[108:111]
	v_mfma_f32_16x16x32_bf16 v[104:107], v[144:147], v[176:179], v[104:107]
	v_mfma_f32_16x16x32_bf16 v[92:95], v[132:135], v[184:187], v[92:95]
	v_mfma_f32_16x16x32_bf16 v[88:91], v[144:147], v[184:187], v[88:91]
	v_mfma_f32_16x16x32_bf16 v[76:79], v[132:135], v[214:217], v[76:79]
	v_mfma_f32_16x16x32_bf16 v[72:75], v[144:147], v[214:217], v[72:75]
	v_mfma_f32_16x16x32_bf16 v[116:119], v[148:151], v[164:167], v[116:119]
	v_mfma_f32_16x16x32_bf16 v[112:115], v[156:159], v[164:167], v[112:115]
	v_mfma_f32_16x16x32_bf16 v[100:103], v[148:151], v[172:175], v[100:103]
	v_mfma_f32_16x16x32_bf16 v[96:99], v[156:159], v[172:175], v[96:99]
	v_mfma_f32_16x16x32_bf16 v[84:87], v[148:151], v[180:183], v[84:87]
	v_mfma_f32_16x16x32_bf16 v[80:83], v[156:159], v[180:183], v[80:83]
	v_mfma_f32_16x16x32_bf16 v[68:71], v[148:151], v[188:191], v[68:71]
	v_mfma_f32_16x16x32_bf16 v[64:67], v[156:159], v[188:191], v[64:67]
	v_mfma_f32_16x16x32_bf16 v[116:119], v[152:155], v[168:171], v[116:119]
	v_mfma_f32_16x16x32_bf16 v[112:115], v[160:163], v[168:171], v[112:115]
	v_mfma_f32_16x16x32_bf16 v[100:103], v[152:155], v[176:179], v[100:103]
	v_mfma_f32_16x16x32_bf16 v[96:99], v[160:163], v[176:179], v[96:99]
	v_mfma_f32_16x16x32_bf16 v[84:87], v[152:155], v[184:187], v[84:87]
	v_mfma_f32_16x16x32_bf16 v[80:83], v[160:163], v[184:187], v[80:83]
	v_mfma_f32_16x16x32_bf16 v[68:71], v[152:155], v[214:217], v[68:71]
	v_mfma_f32_16x16x32_bf16 v[64:67], v[160:163], v[214:217], v[64:67]
	s_setprio 0
	s_barrier
	s_add_i32 s6, s6, s25
	v_lshl_add_u64 v[198:199], s[50:51], 0, v[138:139]
	s_mov_b32 m0, s6
	ds_read_b128 v[164:167], v245 offset:16384
	ds_read_b128 v[168:171], v245 offset:17408
	ds_read_b128 v[172:175], v245 offset:18432
	ds_read_b128 v[176:179], v245 offset:19456
	ds_read_b128 v[180:183], v245 offset:20480
	ds_read_b128 v[184:187], v245 offset:21504
	ds_read_b128 v[188:191], v245 offset:22528
	ds_read_b128 v[214:217], v245 offset:23552
	global_load_lds_dwordx4 v[198:199], off
	s_add_i32 m0, s6, 0x2000
	s_add_u32 s6, s50, 0x2000
	v_lshl_add_u64 v[198:199], s[50:51], 0, v[136:137]
	s_addc_u32 s7, s51, 0
	s_add_i32 s48, s86, s25
	global_load_lds_dwordx4 v[198:199], off
	v_lshl_add_u64 v[198:199], s[6:7], 0, v[138:139]
	s_mov_b32 m0, s48
	v_lshl_add_u64 v[200:201], s[52:53], 0, v[206:207]
	global_load_lds_dwordx4 v[198:199], off
	v_lshl_add_u64 v[198:199], s[6:7], 0, v[136:137]
	s_add_i32 m0, s48, 0x2000
	s_nop 0
	global_load_lds_dwordx4 v[198:199], off
	v_lshl_add_u64 v[198:199], s[52:53], 0, v[208:209]
	s_mov_b32 m0, s12
	s_nop 0
	global_load_lds_dwordx4 v[198:199], off
	s_mov_b32 m0, s13
	s_nop 0
	global_load_lds_dwordx4 v[200:201], off
	s_waitcnt vmcnt(9)
	s_waitcnt lgkmcnt(0)
	s_barrier
; #define PG8_STAGE(bufoff, gbase, voff) do { _Pragma("unroll") for (int _i = 0; _i < 2; ++_i) \
;         __builtin_amdgcn_global_load_lds((const unsigned*)((const char*)(gbase) + (voff)[_i]), (LAS unsigned*)(lds + (bufoff) + ldsw + _i * 8192), 16, 0, 0); } while (0)
; #define PG8_LDA(dst, b, h) do { _Pragma("unroll") for (int m = 0; m < 4; ++m) _Pragma("unroll") for (int k = 0; k < 2; ++k) dst[m][k] = *(const LAS bf16x8*)(lds + PG8_SA(b, h) + aoff + m * 2048 + k * 1024); } while (0)
; #define PG8_LDB(dst, b, h) do { _Pragma("unroll") for (int n = 0; n < 2; ++n) _Pragma("unroll") for (int k = 0; k < 2; ++k) dst[n][k] = *(const LAS bf16x8*)(lds + PG8_SB(b, h) + boff + n * 2048 + k * 1024); } while (0)
; #define PG8_MMA(ai, bj, At, Bt) do { __builtin_amdgcn_s_setprio(1); _Pragma("unroll") for (int m = 0; m < 4; ++m) _Pragma("unroll") for (int n = 0; n < 2; ++n) _Pragma("unroll") for (int k = 0; k < 2; ++k) \
;         acc[ai][bj][m][n] = __builtin_amdgcn_mfma_f32_16x16x32_bf16(Bt[n][k], At[m][k], acc[ai][bj][m][n], 0, 0, 0); __builtin_amdgcn_s_setprio(0); } while (0)
; #define PG8_WAIT_V(n) asm volatile("s_waitcnt vmcnt(" #n ")" ::: "memory")
; #define PG8_WAIT_L(n) asm volatile("s_waitcnt lgkmcnt(" #n ")" ::: "memory")
; #define PG8_BAR __builtin_amdgcn_s_barrier()
; #define PG8_SCHED __builtin_amdgcn_sched_barrier(0)
; template <class Epi, bool ALIGN_EPI>
; __device__ __forceinline__ void gemm_phase(LAS unsigned char* lds, const Gemm g, int G, int cid, const Epi& E) {
;     ...
;             PG8_WAIT_V(8); PG8_WAIT_L(0); PG8_BAR; PG8_MMA(1, 0, At, B0); PG8_MMA(1, 1, At, B1); PG8_BAR; PG8_SCHED;
;             PG8_LDB(B0, 1, 0); PG8_LDB(B1, 1, 1); PG8_SCHED; PG8_LDA(At, 1, 0); PG8_STAGE(PG8_SA(0, 1), a2 + hA, voffA);
;             PG8_WAIT_V(8); PG8_WAIT_L(0); PG8_BAR; PG8_MMA(0, 0, At, B0); PG8_MMA(0, 1, At, B1); PG8_BAR; PG8_SCHED;
	s_setprio 1
	s_waitcnt lgkmcnt(0)
	v_mfma_f32_16x16x32_bf16 v[60:63], v[128:131], v[164:167], v[60:63]
	v_mfma_f32_16x16x32_bf16 v[56:59], v[140:143], v[164:167], v[56:59]
	v_mfma_f32_16x16x32_bf16 v[44:47], v[128:131], v[172:175], v[44:47]
	v_mfma_f32_16x16x32_bf16 v[40:43], v[140:143], v[172:175], v[40:43]
	v_mfma_f32_16x16x32_bf16 v[28:31], v[128:131], v[180:183], v[28:31]
	v_mfma_f32_16x16x32_bf16 v[24:27], v[140:143], v[180:183], v[24:27]
	v_mfma_f32_16x16x32_bf16 v[12:15], v[128:131], v[188:191], v[12:15]
	v_mfma_f32_16x16x32_bf16 v[8:11], v[140:143], v[188:191], v[8:11]
	v_mfma_f32_16x16x32_bf16 v[60:63], v[132:135], v[168:171], v[60:63]
	v_mfma_f32_16x16x32_bf16 v[56:59], v[144:147], v[168:171], v[56:59]
	v_mfma_f32_16x16x32_bf16 v[44:47], v[132:135], v[176:179], v[44:47]
	v_mfma_f32_16x16x32_bf16 v[40:43], v[144:147], v[176:179], v[40:43]
	v_mfma_f32_16x16x32_bf16 v[28:31], v[132:135], v[184:187], v[28:31]
	v_mfma_f32_16x16x32_bf16 v[24:27], v[144:147], v[184:187], v[24:27]
	v_mfma_f32_16x16x32_bf16 v[12:15], v[132:135], v[214:217], v[12:15]
	v_mfma_f32_16x16x32_bf16 v[8:11], v[144:147], v[214:217], v[8:11]
	v_mfma_f32_16x16x32_bf16 v[52:55], v[148:151], v[164:167], v[52:55]
	v_mfma_f32_16x16x32_bf16 v[48:51], v[156:159], v[164:167], v[48:51]
	v_mfma_f32_16x16x32_bf16 v[36:39], v[148:151], v[172:175], v[36:39]
	v_mfma_f32_16x16x32_bf16 v[32:35], v[156:159], v[172:175], v[32:35]
	v_mfma_f32_16x16x32_bf16 v[20:23], v[148:151], v[180:183], v[20:23]
	v_mfma_f32_16x16x32_bf16 v[16:19], v[156:159], v[180:183], v[16:19]
	v_mfma_f32_16x16x32_bf16 v[4:7], v[148:151], v[188:191], v[4:7]
	v_mfma_f32_16x16x32_bf16 v[0:3], v[156:159], v[188:191], v[0:3]
	v_mfma_f32_16x16x32_bf16 v[52:55], v[152:155], v[168:171], v[52:55]
	v_mfma_f32_16x16x32_bf16 v[48:51], v[160:163], v[168:171], v[48:51]
	v_mfma_f32_16x16x32_bf16 v[36:39], v[152:155], v[176:179], v[36:39]
	v_mfma_f32_16x16x32_bf16 v[32:35], v[160:163], v[176:179], v[32:35]
	v_mfma_f32_16x16x32_bf16 v[20:23], v[152:155], v[184:187], v[20:23]
	v_mfma_f32_16x16x32_bf16 v[16:19], v[160:163], v[184:187], v[16:19]
	v_mfma_f32_16x16x32_bf16 v[4:7], v[152:155], v[214:217], v[4:7]
	v_mfma_f32_16x16x32_bf16 v[0:3], v[160:163], v[214:217], v[0:3]
	s_setprio 0
	s_barrier
	s_add_i32 s48, 0, 0x18000
	s_add_i32 s49, 0, 0x1c000
	v_add_u32_e32 v144, s48, v243
	v_add_u32_e32 v160, s49, v243
	ds_read_b128 v[128:131], v144
	ds_read_b128 v[132:135], v144 offset:1024
	ds_read_b128 v[140:143], v144 offset:2048
	ds_read_b128 v[144:147], v144 offset:3072
	ds_read_b128 v[148:151], v160
	ds_read_b128 v[152:155], v160 offset:1024
	ds_read_b128 v[156:159], v160 offset:2048
	ds_read_b128 v[160:163], v160 offset:3072
	s_add_u32 s6, s52, 0x160000
	s_addc_u32 s7, s53, 0
	s_mov_b32 m0, s54
	v_lshl_add_u64 v[218:219], s[6:7], 0, v[208:209]
	ds_read_b128 v[164:167], v245 offset:32768
	ds_read_b128 v[168:171], v245 offset:33792
	ds_read_b128 v[172:175], v245 offset:34816
	ds_read_b128 v[176:179], v245 offset:35840
	ds_read_b128 v[180:183], v245 offset:36864
	ds_read_b128 v[184:187], v245 offset:37888
	ds_read_b128 v[188:191], v245 offset:38912
	ds_read_b128 v[214:217], v245 offset:39936
	global_load_lds_dwordx4 v[218:219], off
	v_lshl_add_u64 v[218:219], s[6:7], 0, v[206:207]
	s_mov_b32 m0, s55
	s_nop 0
	global_load_lds_dwordx4 v[218:219], off
	s_waitcnt vmcnt(8)
	s_waitcnt lgkmcnt(0)
	s_barrier
	s_setprio 1
	s_waitcnt lgkmcnt(0)
	v_mfma_f32_16x16x32_bf16 v[124:127], v[128:131], v[164:167], v[124:127]
	v_mfma_f32_16x16x32_bf16 v[120:123], v[140:143], v[164:167], v[120:123]
	v_mfma_f32_16x16x32_bf16 v[108:111], v[128:131], v[172:175], v[108:111]
	v_mfma_f32_16x16x32_bf16 v[104:107], v[140:143], v[172:175], v[104:107]
	v_mfma_f32_16x16x32_bf16 v[92:95], v[128:131], v[180:183], v[92:95]
	v_mfma_f32_16x16x32_bf16 v[88:91], v[140:143], v[180:183], v[88:91]
	v_mfma_f32_16x16x32_bf16 v[76:79], v[128:131], v[188:191], v[76:79]
	v_mfma_f32_16x16x32_bf16 v[72:75], v[140:143], v[188:191], v[72:75]
	v_mfma_f32_16x16x32_bf16 v[124:127], v[132:135], v[168:171], v[124:127]
	v_mfma_f32_16x16x32_bf16 v[120:123], v[144:147], v[168:171], v[120:123]
	v_mfma_f32_16x16x32_bf16 v[108:111], v[132:135], v[176:179], v[108:111]
	v_mfma_f32_16x16x32_bf16 v[104:107], v[144:147], v[176:179], v[104:107]
	v_mfma_f32_16x16x32_bf16 v[92:95], v[132:135], v[184:187], v[92:95]
	v_mfma_f32_16x16x32_bf16 v[88:91], v[144:147], v[184:187], v[88:91]
	v_mfma_f32_16x16x32_bf16 v[76:79], v[132:135], v[214:217], v[76:79]
	v_mfma_f32_16x16x32_bf16 v[72:75], v[144:147], v[214:217], v[72:75]
	v_mfma_f32_16x16x32_bf16 v[116:119], v[148:151], v[164:167], v[116:119]
	v_mfma_f32_16x16x32_bf16 v[112:115], v[156:159], v[164:167], v[112:115]
	v_mfma_f32_16x16x32_bf16 v[100:103], v[148:151], v[172:175], v[100:103]
	v_mfma_f32_16x16x32_bf16 v[96:99], v[156:159], v[172:175], v[96:99]
	v_mfma_f32_16x16x32_bf16 v[84:87], v[148:151], v[180:183], v[84:87]
	v_mfma_f32_16x16x32_bf16 v[80:83], v[156:159], v[180:183], v[80:83]
	v_mfma_f32_16x16x32_bf16 v[68:71], v[148:151], v[188:191], v[68:71]
	v_mfma_f32_16x16x32_bf16 v[64:67], v[156:159], v[188:191], v[64:67]
	v_mfma_f32_16x16x32_bf16 v[116:119], v[152:155], v[168:171], v[116:119]
	v_mfma_f32_16x16x32_bf16 v[112:115], v[160:163], v[168:171], v[112:115]
	v_mfma_f32_16x16x32_bf16 v[100:103], v[152:155], v[176:179], v[100:103]
	v_mfma_f32_16x16x32_bf16 v[96:99], v[160:163], v[176:179], v[96:99]
	v_mfma_f32_16x16x32_bf16 v[84:87], v[152:155], v[184:187], v[84:87]
	v_mfma_f32_16x16x32_bf16 v[80:83], v[160:163], v[184:187], v[80:83]
	v_mfma_f32_16x16x32_bf16 v[68:71], v[152:155], v[214:217], v[68:71]
	v_mfma_f32_16x16x32_bf16 v[64:67], v[160:163], v[214:217], v[64:67]
	s_setprio 0
	s_barrier
; #define PG8_BAR __builtin_amdgcn_s_barrier()
; template <class Epi, bool ALIGN_EPI>
; __device__ __forceinline__ void gemm_phase(LAS unsigned char* lds, const Gemm g, int G, int cid, const Epi& E) {
;     ...
;             PG8_WAIT_V(8); PG8_WAIT_L(0); PG8_BAR; PG8_MMA(0, 0, At, B0); PG8_MMA(0, 1, At, B1); PG8_BAR; PG8_SCHED;
;             PG8_LDA(At, 1, 1); PG8_STAGE(PG8_SB(1, 0), b3, voffB); PG8_STAGE(PG8_SB(1, 1), b3 + hB, voffB); PG8_STAGE(PG8_SA(1, 0), a3, voffA);
;             PG8_WAIT_V(8); PG8_WAIT_L(0); PG8_BAR; PG8_MMA(1, 0, At, B0); PG8_MMA(1, 1, At, B1); PG8_BAR; PG8_SCHED;
;         }
;     __device__ __forceinline__ void operator()(const f32x4 (&acc)[2][2][4][2], const Unit& u, int wr, int wc, int fr, int fq, const LAS float*) const {
;         const int row0 = u.pm * BM + wr * 64 + fr, col0 = u.pn * BM + wc * 32 + 8 * fq;
;         f32x4 bv[2][2], sv[2][2];
; #pragma unroll
;         for (int bj = 0; bj < 2; ++bj)
; #pragma unroll
;             for (int n = 0; n < 2; ++n) { bv[bj][n] = HB ? *(const f32x4*)(bias + col0 + bj * HALF + 4 * n) : (f32x4){0.f, 0.f, 0.f, 0.f};
;                                            sv[bj][n] = HB ? *(const f32x4*)(scale + col0 + bj * HALF + 4 * n) : (f32x4){1.f, 1.f, 1.f, 1.f}; }
;         constexpr int NB = HB ? 4 : 2, MB = 4 / (NB / 2);
; #pragma unroll
;         for (int am = 0; am < NB; ++am) { const int ai = am / (NB / 2), m0 = (am % (NB / 2)) * MB;
;             f32x4 xo[4][2][2];
; #pragma unroll
;             for (int m = m0; m < m0 + MB; ++m) { const float* xr = Xs + (size_t)(row0 + ai * HALF + m * 16) * DM + col0;
; #pragma unroll
;                 for (int bj = 0; bj < 2; ++bj) { xo[m][bj][0] = *(const f32x4*)(xr + bj * HALF); xo[m][bj][1] = *(const f32x4*)(xr + bj * HALF + 4); } }
; #pragma unroll
;             for (int m = m0; m < m0 + MB; ++m) { const int row = row0 + ai * HALF + m * 16; float ss = 0.f;
;                 float* xr = X + (size_t)row * DM + col0; bf16_t* xb = XB + (size_t)row * ALD + col0;
; #pragma unroll
;                 for (int bj = 0; bj < 2; ++bj) { f32x4 x0 = xo[m][bj][0], x1 = xo[m][bj][1];
;                     if (HB) { x0 += (acc[ai][bj][m][0] + bv[bj][0]) * sv[bj][0]; x1 += (acc[ai][bj][m][1] + bv[bj][1]) * sv[bj][1]; } else { x0 += acc[ai][bj][m][0]; x1 += acc[ai][bj][m][1]; }
;                     *(f32x4*)(xr + bj * HALF) = x0; *(f32x4*)(xr + bj * HALF + 4) = x1;
	s_add_u32 s6, s50, 0x40000
	s_addc_u32 s7, s51, 0
	s_add_i32 s48, s48, s25
	v_lshl_add_u64 v[218:219], s[6:7], 0, v[138:139]
	s_mov_b32 m0, s48
	ds_read_b128 v[164:167], v245 offset:49152
	ds_read_b128 v[168:171], v245 offset:50176
	ds_read_b128 v[172:175], v245 offset:51200
	ds_read_b128 v[176:179], v245 offset:52224
	ds_read_b128 v[180:183], v245 offset:53248
	ds_read_b128 v[184:187], v245 offset:54272
	ds_read_b128 v[188:191], v245 offset:55296
	ds_read_b128 v[214:217], v245 offset:56320
	global_load_lds_dwordx4 v[218:219], off
	s_add_i32 m0, s48, 0x2000
	v_lshl_add_u64 v[218:219], s[6:7], 0, v[136:137]
	s_add_u32 s6, s50, 0x42000
	s_addc_u32 s7, s51, 0
	s_add_i32 s48, s49, s25
	global_load_lds_dwordx4 v[218:219], off
	v_lshl_add_u64 v[218:219], s[6:7], 0, v[138:139]
	s_mov_b32 m0, s48
	v_lshl_add_u64 v[198:199], v[198:199], 0, s[36:37]
	global_load_lds_dwordx4 v[218:219], off
	v_lshl_add_u64 v[218:219], s[6:7], 0, v[136:137]
	s_add_i32 m0, s48, 0x2000
	s_nop 0
	global_load_lds_dwordx4 v[218:219], off
	s_mov_b32 m0, s57
	s_nop 0
	global_load_lds_dwordx4 v[198:199], off
	v_lshl_add_u64 v[198:199], v[200:201], 0, s[36:37]
	s_mov_b32 m0, s58
	s_nop 0
	global_load_lds_dwordx4 v[198:199], off
	s_waitcnt vmcnt(8)
	s_waitcnt lgkmcnt(0)
	s_barrier
	s_setprio 1
	s_waitcnt lgkmcnt(0)
	v_mfma_f32_16x16x32_bf16 v[60:63], v[128:131], v[164:167], v[60:63]
	v_mfma_f32_16x16x32_bf16 v[56:59], v[140:143], v[164:167], v[56:59]
	v_mfma_f32_16x16x32_bf16 v[44:47], v[128:131], v[172:175], v[44:47]
	v_mfma_f32_16x16x32_bf16 v[40:43], v[140:143], v[172:175], v[40:43]
	v_mfma_f32_16x16x32_bf16 v[28:31], v[128:131], v[180:183], v[28:31]
	v_mfma_f32_16x16x32_bf16 v[24:27], v[140:143], v[180:183], v[24:27]
	v_mfma_f32_16x16x32_bf16 v[12:15], v[128:131], v[188:191], v[12:15]
	v_mfma_f32_16x16x32_bf16 v[8:11], v[140:143], v[188:191], v[8:11]
	v_mfma_f32_16x16x32_bf16 v[60:63], v[132:135], v[168:171], v[60:63]
	v_mfma_f32_16x16x32_bf16 v[56:59], v[144:147], v[168:171], v[56:59]
	v_mfma_f32_16x16x32_bf16 v[44:47], v[132:135], v[176:179], v[44:47]
	v_mfma_f32_16x16x32_bf16 v[40:43], v[144:147], v[176:179], v[40:43]
	v_mfma_f32_16x16x32_bf16 v[28:31], v[132:135], v[184:187], v[28:31]
	v_mfma_f32_16x16x32_bf16 v[24:27], v[144:147], v[184:187], v[24:27]
	v_mfma_f32_16x16x32_bf16 v[12:15], v[132:135], v[214:217], v[12:15]
	v_mfma_f32_16x16x32_bf16 v[8:11], v[144:147], v[214:217], v[8:11]
	v_mfma_f32_16x16x32_bf16 v[52:55], v[148:151], v[164:167], v[52:55]
	v_mfma_f32_16x16x32_bf16 v[48:51], v[156:159], v[164:167], v[48:51]
	v_mfma_f32_16x16x32_bf16 v[36:39], v[148:151], v[172:175], v[36:39]
	v_mfma_f32_16x16x32_bf16 v[32:35], v[156:159], v[172:175], v[32:35]
	v_mfma_f32_16x16x32_bf16 v[20:23], v[148:151], v[180:183], v[20:23]
	v_mfma_f32_16x16x32_bf16 v[16:19], v[156:159], v[180:183], v[16:19]
	v_mfma_f32_16x16x32_bf16 v[4:7], v[148:151], v[188:191], v[4:7]
	v_mfma_f32_16x16x32_bf16 v[0:3], v[156:159], v[188:191], v[0:3]
	v_mfma_f32_16x16x32_bf16 v[52:55], v[152:155], v[168:171], v[52:55]
	v_mfma_f32_16x16x32_bf16 v[48:51], v[160:163], v[168:171], v[48:51]
	v_mfma_f32_16x16x32_bf16 v[36:39], v[152:155], v[176:179], v[36:39]
	v_mfma_f32_16x16x32_bf16 v[32:35], v[160:163], v[176:179], v[32:35]
	v_mfma_f32_16x16x32_bf16 v[20:23], v[152:155], v[184:187], v[20:23]
	v_mfma_f32_16x16x32_bf16 v[16:19], v[160:163], v[184:187], v[16:19]
	v_mfma_f32_16x16x32_bf16 v[4:7], v[152:155], v[214:217], v[4:7]
	v_mfma_f32_16x16x32_bf16 v[0:3], v[160:163], v[214:217], v[0:3]
	s_setprio 0
	s_barrier
	s_add_i32 s79, s79, 2
	s_add_u32 s77, s77, 0x80000
	s_addc_u32 s78, s78, 0
	s_cmpk_gt_u32 s79, 0x55
	s_mov_b64 s[48:49], s[40:41]
	s_cbranch_scc0 .LBB0_927
	v_lshl_or_b32 v214, s74, 8, v244
	v_lshl_add_u32 v216, s75, 8, v197
	v_ashrrev_i32_e32 v215, 31, v214
	v_lshlrev_b64 v[198:199], 2, v[214:215]
	v_ashrrev_i32_e32 v217, 31, v216
	v_or_b32_e32 v226, 16, v216
	v_lshl_add_u64 v[218:219], s[82:83], 0, v[198:199]
	v_lshlrev_b64 v[200:201], 13, v[216:217]
	v_ashrrev_i32_e32 v227, 31, v226
	v_or_b32_e32 v222, 32, v216
	v_or_b32_e32 v220, 48, v216
	v_lshl_add_u64 v[128:129], v[218:219], 0, v[200:201]
	v_lshlrev_b64 v[230:231], 13, v[226:227]
	v_ashrrev_i32_e32 v223, 31, v222
	v_ashrrev_i32_e32 v221, 31, v220
	global_load_dwordx4 v[188:191], v[128:129], off offset:16
	global_load_dwordx4 v[246:249], v[128:129], off
	global_load_dwordx4 v[180:183], v[128:129], off offset:528
	global_load_dwordx4 v[184:187], v[128:129], off offset:512
	v_lshl_add_u64 v[128:129], v[218:219], 0, v[230:231]
	v_lshlrev_b64 v[228:229], 13, v[222:223]
	v_lshlrev_b64 v[224:225], 13, v[220:221]
	global_load_dwordx4 v[172:175], v[128:129], off offset:16
	global_load_dwordx4 v[176:179], v[128:129], off
	global_load_dwordx4 v[164:167], v[128:129], off offset:528
	global_load_dwordx4 v[168:171], v[128:129], off offset:512
	v_lshl_add_u64 v[128:129], v[218:219], 0, v[228:229]
	v_lshl_add_u64 v[132:133], v[218:219], 0, v[224:225]
	global_load_dwordx4 v[156:159], v[128:129], off offset:16
	global_load_dwordx4 v[160:163], v[128:129], off
	global_load_dwordx4 v[148:151], v[128:129], off offset:528
	global_load_dwordx4 v[152:155], v[128:129], off offset:512
	global_load_dwordx4 v[140:143], v[132:133], off offset:16
	global_load_dwordx4 v[144:147], v[132:133], off
	s_nop 0
	global_load_dwordx4 v[128:131], v[132:133], off offset:528
	s_nop 0
	global_load_dwordx4 v[132:135], v[132:133], off offset:512
	v_lshl_add_u64 v[200:201], s[82:83], 0, v[200:201]
	v_lshl_add_u64 v[234:235], v[200:201], 0, v[198:199]
	v_mov_b64_e32 v[198:199], s[4:5]
	v_mad_i64_i32 v[198:199], s[6:7], v216, s66, v[198:199]
	v_lshl_add_u64 v[232:233], v[214:215], 1, v[198:199]
	s_and_b64 vcc, exec, s[28:29]
	s_waitcnt vmcnt(12)
	v_pk_add_f32 v[122:123], v[122:123], v[190:191]
	v_pk_add_f32 v[126:127], v[126:127], v[248:249]
	v_pk_add_f32 v[124:125], v[124:125], v[246:247]
	v_pk_add_f32 v[120:121], v[120:121], v[188:189]
	global_store_dwordx4 v[234:235], v[124:127], off
	global_store_dwordx4 v[234:235], v[120:123], off offset:16
	v_cvt_pk_bf16_f32 v188, v124, v125
	v_cvt_pk_bf16_f32 v189, v126, v127
	v_cvt_pk_bf16_f32 v190, v120, v121
	v_cvt_pk_bf16_f32 v191, v122, v123
	s_cbranch_vccz .LBB0_930
	global_store_dwordx4 v[232:233], v[188:191], off
